# v22 + gate/up epilogue for sample-row units: each sub-step's two conv-state loads issued one sub-step earlier on an alternate register set (sub-steps no longer wait for the previous sub-step's stores)
# baseline (speedup 1.0000x reference)
; __device__ __forceinline__ unsigned cvt_pk_bf16(float lo, float hi) { f32x2_t v = {lo, hi}; bf16x2_t b = __builtin_convertvector(v, bf16x2_t); return __builtin_bit_cast(unsigned, b); }
; __device__ __forceinline__ float sigm(float x) { return __builtin_amdgcn_rcpf(1.0f + __builtin_amdgcn_exp2f(-x * LOG2E)); }
;     __device__ __forceinline__ void operator()(const f32x4 (&acc)[2][2][4][2], const Unit& u, int wr, int wc, int fr, int fq) const {
;     ...
;                     for (int m = 0; m < 4; ++m) {
;                         const int row = row0 + ai * HALF + m * 16, rl = row - MPR, bs = rl >> 2, t = rl & 3;
;                         const f32x4 a = acc[ai][0][m][n] * rs[ai][m], uu = acc[ai][1][m][n] * rs[ai][m]; f32x4 gg, s0 = {0.f, 0.f, 0.f, 0.f}, s1 = {0.f, 0.f, 0.f, 0.f};
;                         const float* sc = sconv + (size_t)bs * 2 * 2816 + colt + 4 * n;
;                         if (t == 0) s0 = *(const f32x4*)sc;
;                         if (t <= 1) s1 = *(const f32x4*)(sc + 2816);
; #pragma unroll
;                         for (int j = 0; j < 4; ++j) {
;                             const float up1 = __shfl_up(a[j], 1, 16), up2 = __shfl_up(a[j], 2, 16);
;                             const float p1 = t == 0 ? s1[j] : up1, p2 = t == 0 ? s0[j] : (t == 1 ? s1[j] : up2);
;                             const float c = bb[j] + w0[j] * p2 + w1[j] * p1 + w2[j] * a[j];
;                             gg[j] = c * sigm(c) * uu[j];
;                         }
;                         *(u32x2*)(G + (size_t)row * 2816 + colt + 4 * n) = (u32x2){cvt_pk_bf16(gg[0], gg[1]), cvt_pk_bf16(gg[2], gg[3])};
;                         if (t >= 2) *(f32x4*)(ocs + (size_t)(bs * 2 + t - 2) * 2816 + colt + 4 * n) = a;
;                     }
.LBB0_900:
	s_or_b64 exec, exec, s[8:9]
	v_add_u32_e32 v246, 0xffffc010, v192
	v_ashrrev_i32_e32 v246, 2, v246
	v_mov_b64_e32 v[248:249], s[26:27]
	v_mad_i64_i32 v[248:249], s[20:21], v246, s46, v[248:249]
	v_lshl_add_u64 v[246:247], v[168:169], 2, v[248:249]
	v_add_co_u32_e32 v250, vcc, 0x2000, v246
	s_nop 1
	v_addc_co_u32_e32 v251, vcc, 0, v247, vcc
	s_mov_b64 s[88:89], exec
	s_andn2_b64 exec, s[88:89], s[6:7]
	v_mov_b32_e32 v246, 0
	v_mov_b32_e32 v247, 0
	v_mov_b32_e32 v248, 0
	v_mov_b32_e32 v249, 0
	s_and_b64 exec, s[88:89], s[6:7]
	global_load_dwordx4 v[246:249], v[246:247], off
	s_andn2_b64 exec, s[88:89], s[12:13]
	v_mov_b32_e32 v250, 0
	v_mov_b32_e32 v251, 0
	v_mov_b32_e32 v252, 0
	v_mov_b32_e32 v253, 0
	s_and_b64 exec, s[88:89], s[12:13]
	global_load_dwordx4 v[250:253], v[250:251], off offset:3072
	s_mov_b64 exec, s[88:89]
	v_add_u32_e32 v154, -1, v1
	v_and_b32_e32 v155, 0x70, v1
	v_cmp_lt_i32_e32 vcc, v154, v155
	v_cmp_eq_u32_e64 s[10:11], 1, v156
	v_cmp_lt_u32_e64 s[8:9], 1, v156
	v_cndmask_b32_e32 v154, v154, v1, vcc
	v_lshlrev_b32_e32 v240, 2, v154
	v_add_u32_e32 v154, -2, v1
	v_cmp_lt_i32_e32 vcc, v154, v155
	v_lshl_add_u32 v171, v171, 1, v179
	s_nop 0
	v_cndmask_b32_e32 v157, v154, v1, vcc
	v_pk_mul_f32 v[154:155], v[126:127], v[184:185] op_sel_hi:[1,0]
	v_lshlrev_b32_e32 v241, 2, v157
	ds_bpermute_b32 v175, v240, v154
	ds_bpermute_b32 v157, v241, v154
	ds_bpermute_b32 v173, v240, v155
	ds_bpermute_b32 v177, v241, v155
	s_waitcnt vmcnt(2) lgkmcnt(3)
	v_cndmask_b32_e64 v196, v175, v150, s[6:7]
	s_waitcnt lgkmcnt(2)
	v_cndmask_b32_e64 v150, v157, v150, s[10:11]
	v_pk_mul_f32 v[156:157], v[128:129], v[184:185] op_sel_hi:[1,0]
	s_waitcnt lgkmcnt(1)
	v_cndmask_b32_e64 v197, v173, v151, s[6:7]
	s_waitcnt lgkmcnt(0)
	v_cndmask_b32_e64 v151, v177, v151, s[10:11]
	ds_bpermute_b32 v173, v240, v157
	ds_bpermute_b32 v175, v240, v156
	ds_bpermute_b32 v177, v241, v156
	ds_bpermute_b32 v181, v241, v157
	v_cndmask_b32_e64 v147, v151, v147, s[6:7]
	v_cndmask_b32_e64 v146, v150, v146, s[6:7]
	v_pk_fma_f32 v[146:147], v[130:131], v[146:147], v[142:143]
	s_nop 0
	v_pk_fma_f32 v[146:147], v[134:135], v[196:197], v[146:147]
	s_waitcnt lgkmcnt(3)
	v_cndmask_b32_e64 v197, v173, v153, s[6:7]
	s_waitcnt lgkmcnt(2)
	v_cndmask_b32_e64 v196, v175, v152, s[6:7]
	s_waitcnt lgkmcnt(1)
	v_cndmask_b32_e64 v152, v177, v152, s[10:11]
	s_waitcnt lgkmcnt(0)
	v_cndmask_b32_e64 v153, v181, v153, s[10:11]
	v_cndmask_b32_e64 v149, v153, v149, s[6:7]
	v_cndmask_b32_e64 v148, v152, v148, s[6:7]
	v_pk_fma_f32 v[148:149], v[132:133], v[148:149], v[144:145]
	v_pk_fma_f32 v[146:147], v[154:155], v[138:139], v[146:147]
	v_pk_fma_f32 v[148:149], v[136:137], v[196:197], v[148:149]
	v_mul_f32_e32 v150, 0xbfb8aa3b, v146
	v_mul_f32_e32 v151, 0xbfb8aa3b, v147
	v_pk_fma_f32 v[148:149], v[156:157], v[140:141], v[148:149]
	v_exp_f32_e32 v150, v150
	v_exp_f32_e32 v151, v151
	v_mul_f32_e32 v152, 0xbfb8aa3b, v148
	v_mul_f32_e32 v153, 0xbfb8aa3b, v149
	v_exp_f32_e32 v152, v152
	v_exp_f32_e32 v153, v153
	v_add_f32_e32 v150, 1.0, v150
	v_add_f32_e32 v151, 1.0, v151
	v_rcp_f32_e32 v150, v150
	v_rcp_f32_e32 v151, v151
	v_add_f32_e32 v152, 1.0, v152
	v_add_f32_e32 v153, 1.0, v153
	v_rcp_f32_e32 v152, v152
	v_rcp_f32_e32 v153, v153
	v_pk_mul_f32 v[146:147], v[146:147], v[150:151]
	v_pk_mul_f32 v[150:151], v[94:95], v[184:185] op_sel_hi:[1,0]
	v_pk_mul_f32 v[148:149], v[148:149], v[152:153]
	v_pk_mul_f32 v[146:147], v[150:151], v[146:147]
	v_pk_mul_f32 v[150:151], v[96:97], v[184:185] op_sel_hi:[1,0]
	v_cvt_pk_bf16_f32 v146, v146, v147
	v_pk_mul_f32 v[148:149], v[150:151], v[148:149]
	s_nop 0
	v_cvt_pk_bf16_f32 v147, v148, v149
	v_mov_b64_e32 v[148:149], s[42:43]
	v_mad_i64_i32 v[148:149], s[20:21], v192, s47, v[148:149]
	v_lshl_add_u64 v[214:215], v[168:169], 1, v[148:149]
	global_store_dwordx2 v[214:215], v[146:147], off
	s_and_saveexec_b64 s[88:89], s[8:9]
	s_cbranch_execz .LBB0_902
	v_mov_b64_e32 v[146:147], s[66:67]
	v_mad_i64_i32 v[146:147], s[20:21], v171, s48, v[146:147]
	v_lshl_add_u64 v[146:147], v[168:169], 2, v[146:147]
	global_store_dwordx4 v[146:147], v[154:157], off
.LBB0_902:
	s_or_b64 exec, exec, s[88:89]
	v_add_u32_e32 v173, 0xffffc010, v192
	v_ashrrev_i32_e32 v173, 2, v173
	v_mov_b64_e32 v[196:197], s[26:27]
	v_mad_i64_i32 v[196:197], s[20:21], v173, s46, v[196:197]
	v_lshl_add_u64 v[196:197], v[168:169], 2, v[196:197]
	v_add_u32_e32 v146, 0xffffc020, v192
	v_ashrrev_i32_e32 v146, 2, v146
	v_mov_b64_e32 v[148:149], s[26:27]
	v_mad_i64_i32 v[148:149], s[20:21], v146, s46, v[148:149]
	v_lshl_add_u64 v[146:147], v[168:169], 2, v[148:149]
	v_add_co_u32_e32 v150, vcc, 0x2000, v146
	s_nop 1
	v_addc_co_u32_e32 v151, vcc, 0, v147, vcc
	s_mov_b64 s[88:89], exec
	s_andn2_b64 exec, s[88:89], s[6:7]
	v_mov_b32_e32 v146, 0
	v_mov_b32_e32 v147, 0
	v_mov_b32_e32 v148, 0
	v_mov_b32_e32 v149, 0
	s_and_b64 exec, s[88:89], s[6:7]
	global_load_dwordx4 v[146:149], v[146:147], off
	s_andn2_b64 exec, s[88:89], s[12:13]
	v_mov_b32_e32 v150, 0
	v_mov_b32_e32 v151, 0
	v_mov_b32_e32 v152, 0
	v_mov_b32_e32 v153, 0
	s_and_b64 exec, s[88:89], s[12:13]
	global_load_dwordx4 v[150:153], v[150:151], off offset:3072
	s_mov_b64 exec, s[88:89]
	v_pk_mul_f32 v[154:155], v[118:119], v[182:183] op_sel_hi:[1,0]
	ds_bpermute_b32 v156, v240, v155
	ds_bpermute_b32 v175, v240, v154
	ds_bpermute_b32 v177, v241, v154
	ds_bpermute_b32 v181, v241, v155
	v_lshl_add_u32 v173, v173, 1, v179
	s_waitcnt vmcnt(4) lgkmcnt(3)
	v_cndmask_b32_e64 v157, v156, v251, s[6:7]
	s_waitcnt lgkmcnt(2)
	v_cndmask_b32_e64 v156, v175, v250, s[6:7]
	s_waitcnt lgkmcnt(1)
	v_cndmask_b32_e64 v250, v177, v250, s[10:11]
	s_waitcnt lgkmcnt(0)
; __device__ __forceinline__ unsigned cvt_pk_bf16(float lo, float hi) { f32x2_t v = {lo, hi}; bf16x2_t b = __builtin_convertvector(v, bf16x2_t); return __builtin_bit_cast(unsigned, b); }
; __device__ __forceinline__ float sigm(float x) { return __builtin_amdgcn_rcpf(1.0f + __builtin_amdgcn_exp2f(-x * LOG2E)); }
;     __device__ __forceinline__ void operator()(const f32x4 (&acc)[2][2][4][2], const Unit& u, int wr, int wc, int fr, int fq) const {
;     ...
;                     for (int m = 0; m < 4; ++m) {
;                         const int row = row0 + ai * HALF + m * 16, rl = row - MPR, bs = rl >> 2, t = rl & 3;
;                         const f32x4 a = acc[ai][0][m][n] * rs[ai][m], uu = acc[ai][1][m][n] * rs[ai][m]; f32x4 gg, s0 = {0.f, 0.f, 0.f, 0.f}, s1 = {0.f, 0.f, 0.f, 0.f};
;                         const float* sc = sconv + (size_t)bs * 2 * 2816 + colt + 4 * n;
;                         if (t == 0) s0 = *(const f32x4*)sc;
;                         if (t <= 1) s1 = *(const f32x4*)(sc + 2816);
; #pragma unroll
;                         for (int j = 0; j < 4; ++j) {
;                             const float up1 = __shfl_up(a[j], 1, 16), up2 = __shfl_up(a[j], 2, 16);
;                             const float p1 = t == 0 ? s1[j] : up1, p2 = t == 0 ? s0[j] : (t == 1 ? s1[j] : up2);
;                             const float c = bb[j] + w0[j] * p2 + w1[j] * p1 + w2[j] * a[j];
;                             gg[j] = c * sigm(c) * uu[j];
;                         }
;                         *(u32x2*)(G + (size_t)row * 2816 + colt + 4 * n) = (u32x2){cvt_pk_bf16(gg[0], gg[1]), cvt_pk_bf16(gg[2], gg[3])};
;                         if (t >= 2) *(f32x4*)(ocs + (size_t)(bs * 2 + t - 2) * 2816 + colt + 4 * n) = a;
;                     }
	v_cndmask_b32_e64 v251, v181, v251, s[10:11]
	v_cndmask_b32_e64 v247, v251, v247, s[6:7]
	v_cndmask_b32_e64 v246, v250, v246, s[6:7]
	v_pk_fma_f32 v[246:247], v[130:131], v[246:247], v[142:143]
	s_nop 0
	v_pk_fma_f32 v[246:247], v[134:135], v[156:157], v[246:247]
	v_pk_mul_f32 v[156:157], v[120:121], v[182:183] op_sel_hi:[1,0]
	ds_bpermute_b32 v175, v240, v157
	ds_bpermute_b32 v177, v240, v156
	ds_bpermute_b32 v181, v241, v156
	ds_bpermute_b32 v183, v241, v157
	v_pk_fma_f32 v[246:247], v[154:155], v[138:139], v[246:247]
	s_waitcnt lgkmcnt(3)
	v_cndmask_b32_e64 v199, v175, v253, s[6:7]
	s_waitcnt lgkmcnt(2)
	v_cndmask_b32_e64 v198, v177, v252, s[6:7]
	s_waitcnt lgkmcnt(1)
	v_cndmask_b32_e64 v252, v181, v252, s[10:11]
	s_waitcnt lgkmcnt(0)
	v_cndmask_b32_e64 v253, v183, v253, s[10:11]
	v_cndmask_b32_e64 v249, v253, v249, s[6:7]
	v_cndmask_b32_e64 v248, v252, v248, s[6:7]
	v_pk_fma_f32 v[248:249], v[132:133], v[248:249], v[144:145]
	v_mul_f32_e32 v250, 0xbfb8aa3b, v246
	v_pk_fma_f32 v[248:249], v[136:137], v[198:199], v[248:249]
	v_mul_f32_e32 v251, 0xbfb8aa3b, v247
	v_pk_fma_f32 v[248:249], v[156:157], v[140:141], v[248:249]
	v_exp_f32_e32 v250, v250
	v_exp_f32_e32 v251, v251
	v_mul_f32_e32 v252, 0xbfb8aa3b, v248
	v_mul_f32_e32 v253, 0xbfb8aa3b, v249
	v_exp_f32_e32 v252, v252
	v_exp_f32_e32 v253, v253
	v_add_f32_e32 v250, 1.0, v250
	v_add_f32_e32 v251, 1.0, v251
	v_rcp_f32_e32 v250, v250
	v_rcp_f32_e32 v251, v251
	v_add_f32_e32 v252, 1.0, v252
	v_add_f32_e32 v253, 1.0, v253
	v_rcp_f32_e32 v252, v252
	v_rcp_f32_e32 v253, v253
	v_pk_mul_f32 v[246:247], v[246:247], v[250:251]
	v_pk_mul_f32 v[250:251], v[86:87], v[182:183] op_sel_hi:[1,0]
	v_pk_mul_f32 v[248:249], v[248:249], v[252:253]
	v_pk_mul_f32 v[246:247], v[250:251], v[246:247]
	v_pk_mul_f32 v[250:251], v[88:89], v[182:183] op_sel_hi:[1,0]
	v_cvt_pk_bf16_f32 v246, v246, v247
	v_pk_mul_f32 v[248:249], v[250:251], v[248:249]
	s_nop 0
	v_cvt_pk_bf16_f32 v247, v248, v249
	v_mov_b64_e32 v[248:249], s[42:43]
	v_mad_i64_i32 v[248:249], s[20:21], v190, s47, v[248:249]
	v_lshl_add_u64 v[216:217], v[168:169], 1, v[248:249]
	global_store_dwordx2 v[216:217], v[246:247], off
	s_and_saveexec_b64 s[88:89], s[8:9]
	s_cbranch_execz .LBB0_908
	v_mov_b64_e32 v[246:247], s[66:67]
	v_mad_i64_i32 v[246:247], s[20:21], v173, s48, v[246:247]
	v_lshl_add_u64 v[246:247], v[168:169], 2, v[246:247]
	global_store_dwordx4 v[246:247], v[154:157], off
.LBB0_908:
	s_or_b64 exec, exec, s[88:89]
	v_add_u32_e32 v175, 0xffffc020, v192
	v_ashrrev_i32_e32 v175, 2, v175
	v_mov_b64_e32 v[198:199], s[26:27]
	v_mad_i64_i32 v[198:199], s[20:21], v175, s46, v[198:199]
	v_lshl_add_u64 v[198:199], v[168:169], 2, v[198:199]
	v_add_u32_e32 v246, 0xffffc030, v192
	v_ashrrev_i32_e32 v246, 2, v246
	v_mov_b64_e32 v[248:249], s[26:27]
	v_mad_i64_i32 v[248:249], s[20:21], v246, s46, v[248:249]
	v_lshl_add_u64 v[246:247], v[168:169], 2, v[248:249]
	v_add_co_u32_e32 v250, vcc, 0x2000, v246
	s_nop 1
	v_addc_co_u32_e32 v251, vcc, 0, v247, vcc
	s_mov_b64 s[88:89], exec
	s_andn2_b64 exec, s[88:89], s[6:7]
	v_mov_b32_e32 v246, 0
	v_mov_b32_e32 v247, 0
	v_mov_b32_e32 v248, 0
	v_mov_b32_e32 v249, 0
	s_and_b64 exec, s[88:89], s[6:7]
	global_load_dwordx4 v[246:249], v[246:247], off
	s_andn2_b64 exec, s[88:89], s[12:13]
	v_mov_b32_e32 v250, 0
	v_mov_b32_e32 v251, 0
	v_mov_b32_e32 v252, 0
	v_mov_b32_e32 v253, 0
	s_and_b64 exec, s[88:89], s[12:13]
	global_load_dwordx4 v[250:253], v[250:251], off offset:3072
	s_mov_b64 exec, s[88:89]
	v_pk_mul_f32 v[154:155], v[110:111], v[180:181] op_sel_hi:[1,0]
	ds_bpermute_b32 v156, v240, v155
	ds_bpermute_b32 v177, v240, v154
	ds_bpermute_b32 v181, v241, v154
	ds_bpermute_b32 v183, v241, v155
	v_lshl_add_u32 v175, v175, 1, v179
	s_waitcnt vmcnt(4) lgkmcnt(3)
	v_cndmask_b32_e64 v157, v156, v151, s[6:7]
	s_waitcnt lgkmcnt(2)
	v_cndmask_b32_e64 v156, v177, v150, s[6:7]
	s_waitcnt lgkmcnt(1)
	v_cndmask_b32_e64 v150, v181, v150, s[10:11]
	s_waitcnt lgkmcnt(0)
	v_cndmask_b32_e64 v151, v183, v151, s[10:11]
	v_cndmask_b32_e64 v147, v151, v147, s[6:7]
	v_cndmask_b32_e64 v146, v150, v146, s[6:7]
	v_pk_fma_f32 v[146:147], v[130:131], v[146:147], v[142:143]
	s_nop 0
	v_pk_fma_f32 v[146:147], v[134:135], v[156:157], v[146:147]
	v_pk_mul_f32 v[156:157], v[112:113], v[180:181] op_sel_hi:[1,0]
	ds_bpermute_b32 v177, v240, v157
	ds_bpermute_b32 v181, v240, v156
	ds_bpermute_b32 v183, v241, v156
	ds_bpermute_b32 v185, v241, v157
	v_pk_fma_f32 v[146:147], v[154:155], v[138:139], v[146:147]
	s_waitcnt lgkmcnt(3)
	v_cndmask_b32_e64 v201, v177, v153, s[6:7]
	s_waitcnt lgkmcnt(2)
	v_cndmask_b32_e64 v200, v181, v152, s[6:7]
	s_waitcnt lgkmcnt(1)
	v_cndmask_b32_e64 v152, v183, v152, s[10:11]
	s_waitcnt lgkmcnt(0)
	v_cndmask_b32_e64 v153, v185, v153, s[10:11]
	v_cndmask_b32_e64 v149, v153, v149, s[6:7]
	v_cndmask_b32_e64 v148, v152, v148, s[6:7]
	v_pk_fma_f32 v[148:149], v[132:133], v[148:149], v[144:145]
	v_mul_f32_e32 v150, 0xbfb8aa3b, v146
	v_pk_fma_f32 v[148:149], v[136:137], v[200:201], v[148:149]
	v_mul_f32_e32 v151, 0xbfb8aa3b, v147
	v_pk_fma_f32 v[148:149], v[156:157], v[140:141], v[148:149]
	v_exp_f32_e32 v150, v150
	v_exp_f32_e32 v151, v151
	v_mul_f32_e32 v152, 0xbfb8aa3b, v148
	v_mul_f32_e32 v153, 0xbfb8aa3b, v149
	v_exp_f32_e32 v152, v152
	v_exp_f32_e32 v153, v153
	v_add_f32_e32 v150, 1.0, v150
	v_add_f32_e32 v151, 1.0, v151
	v_rcp_f32_e32 v150, v150
	v_rcp_f32_e32 v151, v151
	v_add_f32_e32 v152, 1.0, v152
	v_add_f32_e32 v153, 1.0, v153
	v_rcp_f32_e32 v152, v152
	v_rcp_f32_e32 v153, v153
	v_pk_mul_f32 v[146:147], v[146:147], v[150:151]
	v_pk_mul_f32 v[150:151], v[78:79], v[180:181] op_sel_hi:[1,0]
	v_pk_mul_f32 v[148:149], v[148:149], v[152:153]
	v_pk_mul_f32 v[146:147], v[150:151], v[146:147]
	v_pk_mul_f32 v[150:151], v[80:81], v[180:181] op_sel_hi:[1,0]
	v_cvt_pk_bf16_f32 v146, v146, v147
	v_pk_mul_f32 v[148:149], v[150:151], v[148:149]
	s_nop 0
	v_cvt_pk_bf16_f32 v147, v148, v149
	v_mov_b64_e32 v[148:149], s[42:43]
	v_mad_i64_i32 v[148:149], s[20:21], v188, s47, v[148:149]
	v_lshl_add_u64 v[218:219], v[168:169], 1, v[148:149]
	global_store_dwordx2 v[218:219], v[146:147], off
	s_and_saveexec_b64 s[88:89], s[8:9]
	s_cbranch_execz .LBB0_914
	v_mov_b64_e32 v[146:147], s[66:67]
	v_mad_i64_i32 v[146:147], s[20:21], v175, s48, v[146:147]
	v_lshl_add_u64 v[146:147], v[168:169], 2, v[146:147]
	global_store_dwordx4 v[146:147], v[154:157], off
; __device__ __forceinline__ unsigned cvt_pk_bf16(float lo, float hi) { f32x2_t v = {lo, hi}; bf16x2_t b = __builtin_convertvector(v, bf16x2_t); return __builtin_bit_cast(unsigned, b); }
; __device__ __forceinline__ float sigm(float x) { return __builtin_amdgcn_rcpf(1.0f + __builtin_amdgcn_exp2f(-x * LOG2E)); }
;     __device__ __forceinline__ void operator()(const f32x4 (&acc)[2][2][4][2], const Unit& u, int wr, int wc, int fr, int fq) const {
;     ...
;                     for (int m = 0; m < 4; ++m) {
;                         const int row = row0 + ai * HALF + m * 16, rl = row - MPR, bs = rl >> 2, t = rl & 3;
;                         const f32x4 a = acc[ai][0][m][n] * rs[ai][m], uu = acc[ai][1][m][n] * rs[ai][m]; f32x4 gg, s0 = {0.f, 0.f, 0.f, 0.f}, s1 = {0.f, 0.f, 0.f, 0.f};
;                         const float* sc = sconv + (size_t)bs * 2 * 2816 + colt + 4 * n;
;                         if (t == 0) s0 = *(const f32x4*)sc;
;                         if (t <= 1) s1 = *(const f32x4*)(sc + 2816);
; #pragma unroll
;                         for (int j = 0; j < 4; ++j) {
;                             const float up1 = __shfl_up(a[j], 1, 16), up2 = __shfl_up(a[j], 2, 16);
;                             const float p1 = t == 0 ? s1[j] : up1, p2 = t == 0 ? s0[j] : (t == 1 ? s1[j] : up2);
;                             const float c = bb[j] + w0[j] * p2 + w1[j] * p1 + w2[j] * a[j];
;                             gg[j] = c * sigm(c) * uu[j];
;                         }
;                         *(u32x2*)(G + (size_t)row * 2816 + colt + 4 * n) = (u32x2){cvt_pk_bf16(gg[0], gg[1]), cvt_pk_bf16(gg[2], gg[3])};
;                         if (t >= 2) *(f32x4*)(ocs + (size_t)(bs * 2 + t - 2) * 2816 + colt + 4 * n) = a;
;                     }
.LBB0_914:
	s_or_b64 exec, exec, s[88:89]
	v_add_u32_e32 v177, 0xffffc030, v192
	v_ashrrev_i32_e32 v177, 2, v177
	v_mov_b64_e32 v[200:201], s[26:27]
	v_mad_i64_i32 v[200:201], s[20:21], v177, s46, v[200:201]
	v_lshl_add_u64 v[200:201], v[168:169], 2, v[200:201]
	v_add_u32_e32 v146, 0xffffc080, v192
	v_ashrrev_i32_e32 v146, 2, v146
	v_mov_b64_e32 v[148:149], s[26:27]
	v_mad_i64_i32 v[148:149], s[20:21], v146, s46, v[148:149]
	v_lshl_add_u64 v[146:147], v[168:169], 2, v[148:149]
	v_add_co_u32_e32 v150, vcc, 0x2000, v146
	s_nop 1
	v_addc_co_u32_e32 v151, vcc, 0, v147, vcc
	s_mov_b64 s[88:89], exec
	s_andn2_b64 exec, s[88:89], s[6:7]
	v_mov_b32_e32 v146, 0
	v_mov_b32_e32 v147, 0
	v_mov_b32_e32 v148, 0
	v_mov_b32_e32 v149, 0
	s_and_b64 exec, s[88:89], s[6:7]
	global_load_dwordx4 v[146:149], v[146:147], off
	s_andn2_b64 exec, s[88:89], s[12:13]
	v_mov_b32_e32 v150, 0
	v_mov_b32_e32 v151, 0
	v_mov_b32_e32 v152, 0
	v_mov_b32_e32 v153, 0
	s_and_b64 exec, s[88:89], s[12:13]
	global_load_dwordx4 v[150:153], v[150:151], off offset:3072
	s_mov_b64 exec, s[88:89]
	v_pk_mul_f32 v[154:155], v[102:103], v[178:179] op_sel_hi:[1,0]
	ds_bpermute_b32 v156, v240, v155
	ds_bpermute_b32 v181, v240, v154
	ds_bpermute_b32 v183, v241, v154
	ds_bpermute_b32 v185, v241, v155
	v_lshl_add_u32 v177, v177, 1, v179
	s_waitcnt vmcnt(4) lgkmcnt(3)
	v_cndmask_b32_e64 v157, v156, v251, s[6:7]
	s_waitcnt lgkmcnt(2)
	v_cndmask_b32_e64 v156, v181, v250, s[6:7]
	s_waitcnt lgkmcnt(1)
	v_cndmask_b32_e64 v250, v183, v250, s[10:11]
	s_waitcnt lgkmcnt(0)
	v_cndmask_b32_e64 v251, v185, v251, s[10:11]
	v_cndmask_b32_e64 v247, v251, v247, s[6:7]
	v_cndmask_b32_e64 v246, v250, v246, s[6:7]
	v_pk_fma_f32 v[246:247], v[130:131], v[246:247], v[142:143]
	s_nop 0
	v_pk_fma_f32 v[246:247], v[134:135], v[156:157], v[246:247]
	v_pk_mul_f32 v[156:157], v[104:105], v[178:179] op_sel_hi:[1,0]
	ds_bpermute_b32 v181, v240, v157
	ds_bpermute_b32 v183, v240, v156
	ds_bpermute_b32 v185, v241, v156
	ds_bpermute_b32 v208, v241, v157
	v_pk_fma_f32 v[246:247], v[154:155], v[138:139], v[246:247]
	s_waitcnt lgkmcnt(3)
	v_cndmask_b32_e64 v205, v181, v253, s[6:7]
	s_waitcnt lgkmcnt(2)
	v_cndmask_b32_e64 v204, v183, v252, s[6:7]
	s_waitcnt lgkmcnt(1)
	v_cndmask_b32_e64 v252, v185, v252, s[10:11]
	s_waitcnt lgkmcnt(0)
	v_cndmask_b32_e64 v253, v208, v253, s[10:11]
	v_cndmask_b32_e64 v249, v253, v249, s[6:7]
	v_cndmask_b32_e64 v248, v252, v248, s[6:7]
	v_pk_fma_f32 v[248:249], v[132:133], v[248:249], v[144:145]
	v_mul_f32_e32 v250, 0xbfb8aa3b, v246
	v_pk_fma_f32 v[248:249], v[136:137], v[204:205], v[248:249]
	v_mul_f32_e32 v251, 0xbfb8aa3b, v247
	v_pk_fma_f32 v[248:249], v[156:157], v[140:141], v[248:249]
	v_exp_f32_e32 v250, v250
	v_exp_f32_e32 v251, v251
	v_mul_f32_e32 v252, 0xbfb8aa3b, v248
	v_mul_f32_e32 v253, 0xbfb8aa3b, v249
	v_exp_f32_e32 v252, v252
	v_exp_f32_e32 v253, v253
	v_add_f32_e32 v250, 1.0, v250
	v_add_f32_e32 v251, 1.0, v251
	v_rcp_f32_e32 v250, v250
	v_rcp_f32_e32 v251, v251
	v_add_f32_e32 v252, 1.0, v252
	v_add_f32_e32 v253, 1.0, v253
	v_rcp_f32_e32 v252, v252
	v_rcp_f32_e32 v253, v253
	v_pk_mul_f32 v[246:247], v[246:247], v[250:251]
	v_pk_mul_f32 v[250:251], v[70:71], v[178:179] op_sel_hi:[1,0]
	v_pk_mul_f32 v[248:249], v[248:249], v[252:253]
	v_pk_mul_f32 v[246:247], v[250:251], v[246:247]
	v_pk_mul_f32 v[250:251], v[72:73], v[178:179] op_sel_hi:[1,0]
	v_cvt_pk_bf16_f32 v246, v246, v247
	v_pk_mul_f32 v[248:249], v[250:251], v[248:249]
	s_nop 0
	v_cvt_pk_bf16_f32 v247, v248, v249
	v_mov_b64_e32 v[248:249], s[42:43]
	v_mad_i64_i32 v[248:249], s[20:21], v186, s47, v[248:249]
	v_lshl_add_u64 v[220:221], v[168:169], 1, v[248:249]
	global_store_dwordx2 v[220:221], v[246:247], off
	s_and_saveexec_b64 s[88:89], s[8:9]
	s_cbranch_execz .LBB0_920
	v_mov_b64_e32 v[246:247], s[66:67]
	v_mad_i64_i32 v[246:247], s[20:21], v177, s48, v[246:247]
	v_lshl_add_u64 v[246:247], v[168:169], 2, v[246:247]
	global_store_dwordx4 v[246:247], v[154:157], off
.LBB0_920:
	s_or_b64 exec, exec, s[88:89]
	v_add_u32_e32 v181, 0xffffc080, v192
	v_ashrrev_i32_e32 v181, 2, v181
	v_mov_b64_e32 v[204:205], s[26:27]
	v_mad_i64_i32 v[204:205], s[20:21], v181, s46, v[204:205]
	v_lshl_add_u64 v[204:205], v[168:169], 2, v[204:205]
	v_add_u32_e32 v246, 0xffffc090, v192
	v_ashrrev_i32_e32 v246, 2, v246
	v_mov_b64_e32 v[248:249], s[26:27]
	v_mad_i64_i32 v[248:249], s[20:21], v246, s46, v[248:249]
	v_lshl_add_u64 v[246:247], v[168:169], 2, v[248:249]
	v_add_co_u32_e32 v250, vcc, 0x2000, v246
	s_nop 1
	v_addc_co_u32_e32 v251, vcc, 0, v247, vcc
	s_mov_b64 s[88:89], exec
	s_andn2_b64 exec, s[88:89], s[6:7]
	v_mov_b32_e32 v246, 0
	v_mov_b32_e32 v247, 0
	v_mov_b32_e32 v248, 0
	v_mov_b32_e32 v249, 0
	s_and_b64 exec, s[88:89], s[6:7]
	global_load_dwordx4 v[246:249], v[246:247], off
	s_andn2_b64 exec, s[88:89], s[12:13]
	v_mov_b32_e32 v250, 0
	v_mov_b32_e32 v251, 0
	v_mov_b32_e32 v252, 0
	v_mov_b32_e32 v253, 0
	s_and_b64 exec, s[88:89], s[12:13]
	global_load_dwordx4 v[250:253], v[250:251], off offset:3072
	s_mov_b64 exec, s[88:89]
	v_pk_mul_f32 v[154:155], v[62:63], v[176:177] op_sel_hi:[1,0]
	ds_bpermute_b32 v156, v240, v155
	ds_bpermute_b32 v183, v240, v154
	ds_bpermute_b32 v185, v241, v154
	ds_bpermute_b32 v208, v241, v155
	v_lshl_add_u32 v243, v181, 1, v179
	s_waitcnt vmcnt(4) lgkmcnt(3)
	v_cndmask_b32_e64 v157, v156, v151, s[6:7]
	s_waitcnt lgkmcnt(2)
	v_cndmask_b32_e64 v156, v183, v150, s[6:7]
	s_waitcnt lgkmcnt(1)
	v_cndmask_b32_e64 v150, v185, v150, s[10:11]
	s_waitcnt lgkmcnt(0)
; __device__ __forceinline__ unsigned cvt_pk_bf16(float lo, float hi) { f32x2_t v = {lo, hi}; bf16x2_t b = __builtin_convertvector(v, bf16x2_t); return __builtin_bit_cast(unsigned, b); }
; __device__ __forceinline__ float sigm(float x) { return __builtin_amdgcn_rcpf(1.0f + __builtin_amdgcn_exp2f(-x * LOG2E)); }
;     __device__ __forceinline__ void operator()(const f32x4 (&acc)[2][2][4][2], const Unit& u, int wr, int wc, int fr, int fq) const {
;     ...
;                     for (int m = 0; m < 4; ++m) {
;                         const int row = row0 + ai * HALF + m * 16, rl = row - MPR, bs = rl >> 2, t = rl & 3;
;                         const f32x4 a = acc[ai][0][m][n] * rs[ai][m], uu = acc[ai][1][m][n] * rs[ai][m]; f32x4 gg, s0 = {0.f, 0.f, 0.f, 0.f}, s1 = {0.f, 0.f, 0.f, 0.f};
;                         const float* sc = sconv + (size_t)bs * 2 * 2816 + colt + 4 * n;
;                         if (t == 0) s0 = *(const f32x4*)sc;
;                         if (t <= 1) s1 = *(const f32x4*)(sc + 2816);
; #pragma unroll
;                         for (int j = 0; j < 4; ++j) {
;                             const float up1 = __shfl_up(a[j], 1, 16), up2 = __shfl_up(a[j], 2, 16);
;                             const float p1 = t == 0 ? s1[j] : up1, p2 = t == 0 ? s0[j] : (t == 1 ? s1[j] : up2);
;                             const float c = bb[j] + w0[j] * p2 + w1[j] * p1 + w2[j] * a[j];
;                             gg[j] = c * sigm(c) * uu[j];
;                         }
;                         *(u32x2*)(G + (size_t)row * 2816 + colt + 4 * n) = (u32x2){cvt_pk_bf16(gg[0], gg[1]), cvt_pk_bf16(gg[2], gg[3])};
;                         if (t >= 2) *(f32x4*)(ocs + (size_t)(bs * 2 + t - 2) * 2816 + colt + 4 * n) = a;
;                     }
	v_cndmask_b32_e64 v151, v208, v151, s[10:11]
	v_cndmask_b32_e64 v147, v151, v147, s[6:7]
	v_cndmask_b32_e64 v146, v150, v146, s[6:7]
	v_pk_fma_f32 v[146:147], v[130:131], v[146:147], v[142:143]
	s_nop 0
	v_pk_fma_f32 v[146:147], v[134:135], v[156:157], v[146:147]
	v_pk_mul_f32 v[156:157], v[64:65], v[176:177] op_sel_hi:[1,0]
	ds_bpermute_b32 v183, v240, v157
	ds_bpermute_b32 v185, v240, v156
	ds_bpermute_b32 v210, v241, v156
	ds_bpermute_b32 v211, v241, v157
	v_pk_fma_f32 v[146:147], v[154:155], v[138:139], v[146:147]
	s_waitcnt lgkmcnt(3)
	v_cndmask_b32_e64 v209, v183, v153, s[6:7]
	s_waitcnt lgkmcnt(2)
	v_cndmask_b32_e64 v208, v185, v152, s[6:7]
	s_waitcnt lgkmcnt(1)
	v_cndmask_b32_e64 v152, v210, v152, s[10:11]
	s_waitcnt lgkmcnt(0)
	v_cndmask_b32_e64 v153, v211, v153, s[10:11]
	v_cndmask_b32_e64 v149, v153, v149, s[6:7]
	v_cndmask_b32_e64 v148, v152, v148, s[6:7]
	v_pk_fma_f32 v[148:149], v[132:133], v[148:149], v[144:145]
	v_mul_f32_e32 v150, 0xbfb8aa3b, v146
	v_pk_fma_f32 v[148:149], v[136:137], v[208:209], v[148:149]
	v_mul_f32_e32 v151, 0xbfb8aa3b, v147
	v_pk_fma_f32 v[148:149], v[156:157], v[140:141], v[148:149]
	v_exp_f32_e32 v150, v150
	v_exp_f32_e32 v151, v151
	v_mul_f32_e32 v152, 0xbfb8aa3b, v148
	v_mul_f32_e32 v153, 0xbfb8aa3b, v149
	v_exp_f32_e32 v152, v152
	v_exp_f32_e32 v153, v153
	v_add_f32_e32 v150, 1.0, v150
	v_add_f32_e32 v151, 1.0, v151
	v_rcp_f32_e32 v150, v150
	v_rcp_f32_e32 v151, v151
	v_add_f32_e32 v152, 1.0, v152
	v_add_f32_e32 v153, 1.0, v153
	v_rcp_f32_e32 v152, v152
	v_rcp_f32_e32 v153, v153
	v_pk_mul_f32 v[146:147], v[146:147], v[150:151]
	v_pk_mul_f32 v[150:151], v[30:31], v[176:177] op_sel_hi:[1,0]
	v_pk_mul_f32 v[148:149], v[148:149], v[152:153]
	v_pk_mul_f32 v[146:147], v[150:151], v[146:147]
	v_pk_mul_f32 v[150:151], v[32:33], v[176:177] op_sel_hi:[1,0]
	v_cvt_pk_bf16_f32 v146, v146, v147
	v_pk_mul_f32 v[148:149], v[150:151], v[148:149]
	s_nop 0
	v_cvt_pk_bf16_f32 v147, v148, v149
	v_mov_b64_e32 v[148:149], s[42:43]
	v_mad_i64_i32 v[148:149], s[20:21], v189, s47, v[148:149]
	v_lshl_add_u64 v[222:223], v[168:169], 1, v[148:149]
	global_store_dwordx2 v[222:223], v[146:147], off
	s_and_saveexec_b64 s[88:89], s[8:9]
	s_cbranch_execz .LBB0_926
	v_mov_b64_e32 v[146:147], s[66:67]
	v_mad_i64_i32 v[146:147], s[20:21], v243, s48, v[146:147]
	v_lshl_add_u64 v[146:147], v[168:169], 2, v[146:147]
	global_store_dwordx4 v[146:147], v[154:157], off
.LBB0_926:
	s_or_b64 exec, exec, s[88:89]
	v_add_u32_e32 v181, 0xffffc090, v192
	v_ashrrev_i32_e32 v181, 2, v181
	v_mov_b64_e32 v[208:209], s[26:27]
	v_mad_i64_i32 v[208:209], s[20:21], v181, s46, v[208:209]
	v_lshl_add_u64 v[208:209], v[168:169], 2, v[208:209]
	v_add_u32_e32 v146, 0xffffc0a0, v192
	v_ashrrev_i32_e32 v146, 2, v146
	v_mov_b64_e32 v[148:149], s[26:27]
	v_mad_i64_i32 v[148:149], s[20:21], v146, s46, v[148:149]
	v_lshl_add_u64 v[146:147], v[168:169], 2, v[148:149]
	v_add_co_u32_e32 v150, vcc, 0x2000, v146
	s_nop 1
	v_addc_co_u32_e32 v151, vcc, 0, v147, vcc
	s_mov_b64 s[88:89], exec
	s_andn2_b64 exec, s[88:89], s[6:7]
	v_mov_b32_e32 v146, 0
	v_mov_b32_e32 v147, 0
	v_mov_b32_e32 v148, 0
	v_mov_b32_e32 v149, 0
	s_and_b64 exec, s[88:89], s[6:7]
	global_load_dwordx4 v[146:149], v[146:147], off
	s_andn2_b64 exec, s[88:89], s[12:13]
	v_mov_b32_e32 v150, 0
	v_mov_b32_e32 v151, 0
	v_mov_b32_e32 v152, 0
	v_mov_b32_e32 v153, 0
	s_and_b64 exec, s[88:89], s[12:13]
	global_load_dwordx4 v[150:153], v[150:151], off offset:3072
	s_mov_b64 exec, s[88:89]
	v_pk_mul_f32 v[154:155], v[54:55], v[174:175] op_sel_hi:[1,0]
	ds_bpermute_b32 v156, v240, v155
	ds_bpermute_b32 v183, v240, v154
	ds_bpermute_b32 v185, v241, v154
	ds_bpermute_b32 v210, v241, v155
	v_lshl_add_u32 v244, v181, 1, v179
	s_waitcnt vmcnt(4) lgkmcnt(3)
	v_cndmask_b32_e64 v157, v156, v251, s[6:7]
	s_waitcnt lgkmcnt(2)
	v_cndmask_b32_e64 v156, v183, v250, s[6:7]
	s_waitcnt lgkmcnt(1)
	v_cndmask_b32_e64 v250, v185, v250, s[10:11]
	s_waitcnt lgkmcnt(0)
	v_cndmask_b32_e64 v251, v210, v251, s[10:11]
	v_cndmask_b32_e64 v247, v251, v247, s[6:7]
	v_cndmask_b32_e64 v246, v250, v246, s[6:7]
	v_pk_fma_f32 v[246:247], v[130:131], v[246:247], v[142:143]
	s_nop 0
	v_pk_fma_f32 v[246:247], v[134:135], v[156:157], v[246:247]
	v_pk_mul_f32 v[156:157], v[56:57], v[174:175] op_sel_hi:[1,0]
	ds_bpermute_b32 v183, v240, v157
	ds_bpermute_b32 v185, v240, v156
	ds_bpermute_b32 v212, v241, v156
	ds_bpermute_b32 v213, v241, v157
	v_pk_fma_f32 v[246:247], v[154:155], v[138:139], v[246:247]
	s_waitcnt lgkmcnt(3)
	v_cndmask_b32_e64 v211, v183, v253, s[6:7]
	s_waitcnt lgkmcnt(2)
	v_cndmask_b32_e64 v210, v185, v252, s[6:7]
	s_waitcnt lgkmcnt(1)
	v_cndmask_b32_e64 v252, v212, v252, s[10:11]
	s_waitcnt lgkmcnt(0)
	v_cndmask_b32_e64 v253, v213, v253, s[10:11]
	v_cndmask_b32_e64 v249, v253, v249, s[6:7]
	v_cndmask_b32_e64 v248, v252, v248, s[6:7]
	v_pk_fma_f32 v[248:249], v[132:133], v[248:249], v[144:145]
	v_mul_f32_e32 v250, 0xbfb8aa3b, v246
	v_pk_fma_f32 v[248:249], v[136:137], v[210:211], v[248:249]
	v_mul_f32_e32 v251, 0xbfb8aa3b, v247
	v_pk_fma_f32 v[248:249], v[156:157], v[140:141], v[248:249]
	v_exp_f32_e32 v250, v250
	v_exp_f32_e32 v251, v251
	v_mul_f32_e32 v252, 0xbfb8aa3b, v248
	v_mul_f32_e32 v253, 0xbfb8aa3b, v249
	v_exp_f32_e32 v252, v252
	v_exp_f32_e32 v253, v253
	v_add_f32_e32 v250, 1.0, v250
	v_add_f32_e32 v251, 1.0, v251
	v_rcp_f32_e32 v250, v250
	v_rcp_f32_e32 v251, v251
	v_add_f32_e32 v252, 1.0, v252
	v_add_f32_e32 v253, 1.0, v253
	v_rcp_f32_e32 v252, v252
	v_rcp_f32_e32 v253, v253
	v_pk_mul_f32 v[246:247], v[246:247], v[250:251]
	v_pk_mul_f32 v[250:251], v[22:23], v[174:175] op_sel_hi:[1,0]
	v_pk_mul_f32 v[248:249], v[248:249], v[252:253]
	v_pk_mul_f32 v[246:247], v[250:251], v[246:247]
	v_pk_mul_f32 v[250:251], v[24:25], v[174:175] op_sel_hi:[1,0]
	v_cvt_pk_bf16_f32 v246, v246, v247
	v_pk_mul_f32 v[248:249], v[250:251], v[248:249]
	s_nop 0
	v_cvt_pk_bf16_f32 v247, v248, v249
	v_mov_b64_e32 v[248:249], s[42:43]
	v_mad_i64_i32 v[248:249], s[20:21], v191, s47, v[248:249]
	v_lshl_add_u64 v[224:225], v[168:169], 1, v[248:249]
	global_store_dwordx2 v[224:225], v[246:247], off
	s_and_saveexec_b64 s[88:89], s[8:9]
	s_cbranch_execz .LBB0_932
	v_mov_b64_e32 v[246:247], s[66:67]
	v_mad_i64_i32 v[246:247], s[20:21], v244, s48, v[246:247]
	v_lshl_add_u64 v[246:247], v[168:169], 2, v[246:247]
	global_store_dwordx4 v[246:247], v[154:157], off
; __device__ __forceinline__ unsigned cvt_pk_bf16(float lo, float hi) { f32x2_t v = {lo, hi}; bf16x2_t b = __builtin_convertvector(v, bf16x2_t); return __builtin_bit_cast(unsigned, b); }
; __device__ __forceinline__ float sigm(float x) { return __builtin_amdgcn_rcpf(1.0f + __builtin_amdgcn_exp2f(-x * LOG2E)); }
;     __device__ __forceinline__ void operator()(const f32x4 (&acc)[2][2][4][2], const Unit& u, int wr, int wc, int fr, int fq) const {
;     ...
;                     for (int m = 0; m < 4; ++m) {
;                         const int row = row0 + ai * HALF + m * 16, rl = row - MPR, bs = rl >> 2, t = rl & 3;
;                         const f32x4 a = acc[ai][0][m][n] * rs[ai][m], uu = acc[ai][1][m][n] * rs[ai][m]; f32x4 gg, s0 = {0.f, 0.f, 0.f, 0.f}, s1 = {0.f, 0.f, 0.f, 0.f};
;                         const float* sc = sconv + (size_t)bs * 2 * 2816 + colt + 4 * n;
;                         if (t == 0) s0 = *(const f32x4*)sc;
;                         if (t <= 1) s1 = *(const f32x4*)(sc + 2816);
; #pragma unroll
;                         for (int j = 0; j < 4; ++j) {
;                             const float up1 = __shfl_up(a[j], 1, 16), up2 = __shfl_up(a[j], 2, 16);
;                             const float p1 = t == 0 ? s1[j] : up1, p2 = t == 0 ? s0[j] : (t == 1 ? s1[j] : up2);
;                             const float c = bb[j] + w0[j] * p2 + w1[j] * p1 + w2[j] * a[j];
;                             gg[j] = c * sigm(c) * uu[j];
;                         }
;                         *(u32x2*)(G + (size_t)row * 2816 + colt + 4 * n) = (u32x2){cvt_pk_bf16(gg[0], gg[1]), cvt_pk_bf16(gg[2], gg[3])};
;                         if (t >= 2) *(f32x4*)(ocs + (size_t)(bs * 2 + t - 2) * 2816 + colt + 4 * n) = a;
;                     }
.LBB0_932:
	s_or_b64 exec, exec, s[88:89]
	v_add_u32_e32 v181, 0xffffc0a0, v192
	v_ashrrev_i32_e32 v181, 2, v181
	v_mov_b64_e32 v[210:211], s[26:27]
	v_mad_i64_i32 v[210:211], s[20:21], v181, s46, v[210:211]
	v_lshl_add_u64 v[210:211], v[168:169], 2, v[210:211]
	v_add_u32_e32 v246, 0xffffc0b0, v192
	v_ashrrev_i32_e32 v246, 2, v246
	v_mov_b64_e32 v[248:249], s[26:27]
	v_mad_i64_i32 v[248:249], s[20:21], v246, s46, v[248:249]
	v_lshl_add_u64 v[246:247], v[168:169], 2, v[248:249]
	v_add_co_u32_e32 v250, vcc, 0x2000, v246
	s_nop 1
	v_addc_co_u32_e32 v251, vcc, 0, v247, vcc
	s_mov_b64 s[88:89], exec
	s_andn2_b64 exec, s[88:89], s[6:7]
	v_mov_b32_e32 v246, 0
	v_mov_b32_e32 v247, 0
	v_mov_b32_e32 v248, 0
	v_mov_b32_e32 v249, 0
	s_and_b64 exec, s[88:89], s[6:7]
	global_load_dwordx4 v[246:249], v[246:247], off
	s_andn2_b64 exec, s[88:89], s[12:13]
	v_mov_b32_e32 v250, 0
	v_mov_b32_e32 v251, 0
	v_mov_b32_e32 v252, 0
	v_mov_b32_e32 v253, 0
	s_and_b64 exec, s[88:89], s[12:13]
	global_load_dwordx4 v[250:253], v[250:251], off offset:3072
	s_mov_b64 exec, s[88:89]
	v_pk_mul_f32 v[154:155], v[46:47], v[172:173] op_sel_hi:[1,0]
	ds_bpermute_b32 v156, v240, v155
	ds_bpermute_b32 v183, v240, v154
	ds_bpermute_b32 v185, v241, v154
	ds_bpermute_b32 v212, v241, v155
	v_lshl_add_u32 v245, v181, 1, v179
	s_waitcnt vmcnt(4) lgkmcnt(3)
	v_cndmask_b32_e64 v157, v156, v151, s[6:7]
	s_waitcnt lgkmcnt(2)
	v_cndmask_b32_e64 v156, v183, v150, s[6:7]
	s_waitcnt lgkmcnt(1)
	v_cndmask_b32_e64 v150, v185, v150, s[10:11]
	s_waitcnt lgkmcnt(0)
	v_cndmask_b32_e64 v151, v212, v151, s[10:11]
	v_cndmask_b32_e64 v147, v151, v147, s[6:7]
	v_cndmask_b32_e64 v146, v150, v146, s[6:7]
	v_pk_fma_f32 v[146:147], v[130:131], v[146:147], v[142:143]
	s_nop 0
	v_pk_fma_f32 v[146:147], v[134:135], v[156:157], v[146:147]
	v_pk_mul_f32 v[156:157], v[48:49], v[172:173] op_sel_hi:[1,0]
	ds_bpermute_b32 v183, v240, v157
	ds_bpermute_b32 v185, v240, v156
	ds_bpermute_b32 v226, v241, v156
	ds_bpermute_b32 v227, v241, v157
	v_pk_fma_f32 v[146:147], v[154:155], v[138:139], v[146:147]
	s_waitcnt lgkmcnt(3)
	v_cndmask_b32_e64 v213, v183, v153, s[6:7]
	s_waitcnt lgkmcnt(2)
	v_cndmask_b32_e64 v212, v185, v152, s[6:7]
	s_waitcnt lgkmcnt(1)
	v_cndmask_b32_e64 v152, v226, v152, s[10:11]
	s_waitcnt lgkmcnt(0)
	v_cndmask_b32_e64 v153, v227, v153, s[10:11]
	v_cndmask_b32_e64 v149, v153, v149, s[6:7]
	v_cndmask_b32_e64 v148, v152, v148, s[6:7]
	v_pk_fma_f32 v[148:149], v[132:133], v[148:149], v[144:145]
	v_mul_f32_e32 v150, 0xbfb8aa3b, v146
	v_pk_fma_f32 v[148:149], v[136:137], v[212:213], v[148:149]
	v_mul_f32_e32 v151, 0xbfb8aa3b, v147
	v_pk_fma_f32 v[148:149], v[156:157], v[140:141], v[148:149]
	v_exp_f32_e32 v150, v150
	v_exp_f32_e32 v151, v151
	v_mul_f32_e32 v152, 0xbfb8aa3b, v148
	v_mul_f32_e32 v153, 0xbfb8aa3b, v149
	v_exp_f32_e32 v152, v152
	v_exp_f32_e32 v153, v153
	v_add_f32_e32 v150, 1.0, v150
	v_add_f32_e32 v151, 1.0, v151
	v_rcp_f32_e32 v150, v150
	v_rcp_f32_e32 v151, v151
	v_add_f32_e32 v152, 1.0, v152
	v_add_f32_e32 v153, 1.0, v153
	v_rcp_f32_e32 v152, v152
	v_rcp_f32_e32 v153, v153
	v_pk_mul_f32 v[146:147], v[146:147], v[150:151]
	v_pk_mul_f32 v[150:151], v[14:15], v[172:173] op_sel_hi:[1,0]
	v_pk_mul_f32 v[148:149], v[148:149], v[152:153]
	v_pk_mul_f32 v[146:147], v[150:151], v[146:147]
	v_pk_mul_f32 v[150:151], v[16:17], v[172:173] op_sel_hi:[1,0]
	v_cvt_pk_bf16_f32 v146, v146, v147
	v_pk_mul_f32 v[148:149], v[150:151], v[148:149]
	s_nop 0
	v_cvt_pk_bf16_f32 v147, v148, v149
	v_mov_b64_e32 v[148:149], s[42:43]
	v_mad_i64_i32 v[148:149], s[20:21], v193, s47, v[148:149]
	v_lshl_add_u64 v[226:227], v[168:169], 1, v[148:149]
	global_store_dwordx2 v[226:227], v[146:147], off
	s_and_saveexec_b64 s[88:89], s[8:9]
	s_cbranch_execz .LBB0_938
	v_mov_b64_e32 v[146:147], s[66:67]
	v_mad_i64_i32 v[146:147], s[20:21], v245, s48, v[146:147]
	v_lshl_add_u64 v[146:147], v[168:169], 2, v[146:147]
	global_store_dwordx4 v[146:147], v[154:157], off
.LBB0_938:
	s_or_b64 exec, exec, s[88:89]
	v_add_u32_e32 v181, 0xffffc0b0, v192
	v_ashrrev_i32_e32 v181, 2, v181
	v_mov_b64_e32 v[212:213], s[26:27]
	v_mad_i64_i32 v[212:213], s[20:21], v181, s46, v[212:213]
	v_lshl_add_u64 v[212:213], v[168:169], 2, v[212:213]
	v_add_co_u32_e32 v150, vcc, 0x2000, v194
	s_nop 1
	v_addc_co_u32_e32 v151, vcc, 0, v195, vcc
	s_mov_b64 s[88:89], exec
	s_andn2_b64 exec, s[88:89], s[6:7]
	v_mov_b32_e32 v146, 0
	v_mov_b32_e32 v147, 0
	v_mov_b32_e32 v148, 0
	v_mov_b32_e32 v149, 0
	s_and_b64 exec, s[88:89], s[6:7]
	global_load_dwordx4 v[146:149], v[194:195], off offset:16
	s_andn2_b64 exec, s[88:89], s[12:13]
	v_mov_b32_e32 v150, 0
	v_mov_b32_e32 v151, 0
	v_mov_b32_e32 v152, 0
	v_mov_b32_e32 v153, 0
	s_and_b64 exec, s[88:89], s[12:13]
	global_load_dwordx4 v[150:153], v[150:151], off offset:3088
	s_mov_b64 exec, s[88:89]
	v_pk_mul_f32 v[154:155], v[38:39], v[170:171] op_sel_hi:[1,0]
	ds_bpermute_b32 v156, v240, v155
	ds_bpermute_b32 v183, v240, v154
	ds_bpermute_b32 v185, v241, v154
	ds_bpermute_b32 v228, v241, v155
	v_lshl_add_u32 v242, v181, 1, v179
	s_waitcnt vmcnt(4) lgkmcnt(3)
	v_cndmask_b32_e64 v157, v156, v251, s[6:7]
	s_waitcnt lgkmcnt(2)
	v_cndmask_b32_e64 v156, v183, v250, s[6:7]
	s_waitcnt lgkmcnt(1)
	v_cndmask_b32_e64 v250, v185, v250, s[10:11]
	s_waitcnt lgkmcnt(0)
	v_cndmask_b32_e64 v251, v228, v251, s[10:11]
	v_cndmask_b32_e64 v247, v251, v247, s[6:7]
	v_cndmask_b32_e64 v246, v250, v246, s[6:7]
	v_pk_fma_f32 v[130:131], v[130:131], v[246:247], v[142:143]
	s_nop 0
	v_pk_fma_f32 v[130:131], v[134:135], v[156:157], v[130:131]
	v_pk_mul_f32 v[156:157], v[40:41], v[170:171] op_sel_hi:[1,0]
	v_pk_fma_f32 v[130:131], v[154:155], v[138:139], v[130:131]
	ds_bpermute_b32 v138, v240, v157
	ds_bpermute_b32 v142, v240, v156
	ds_bpermute_b32 v143, v241, v156
	ds_bpermute_b32 v246, v241, v157
	v_mul_f32_e32 v134, 0xbfb8aa3b, v130
	s_waitcnt lgkmcnt(3)
; __device__ __forceinline__ unsigned cvt_pk_bf16(float lo, float hi) { f32x2_t v = {lo, hi}; bf16x2_t b = __builtin_convertvector(v, bf16x2_t); return __builtin_bit_cast(unsigned, b); }
; __device__ __forceinline__ float sigm(float x) { return __builtin_amdgcn_rcpf(1.0f + __builtin_amdgcn_exp2f(-x * LOG2E)); }
;     __device__ __forceinline__ void operator()(const f32x4 (&acc)[2][2][4][2], const Unit& u, int wr, int wc, int fr, int fq) const {
;     ...
;             for (int n = 0; n < 2; ++n) {
;                 const f32x4 w0 = *(const f32x4*)(cw + colt + 4 * n), w1 = *(const f32x4*)(cw + 2816 + colt + 4 * n), w2 = *(const f32x4*)(cw + 5632 + colt + 4 * n), bb = *(const f32x4*)(cb + colt + 4 * n);
; #pragma unroll
;                 for (int ai = 0; ai < 2; ++ai)
; #pragma unroll
;                     for (int m = 0; m < 4; ++m) {
;                         const int row = row0 + ai * HALF + m * 16, rl = row - MPR, bs = rl >> 2, t = rl & 3;
;                         const f32x4 a = acc[ai][0][m][n] * rs[ai][m], uu = acc[ai][1][m][n] * rs[ai][m]; f32x4 gg, s0 = {0.f, 0.f, 0.f, 0.f}, s1 = {0.f, 0.f, 0.f, 0.f};
;                         const float* sc = sconv + (size_t)bs * 2 * 2816 + colt + 4 * n;
;                         if (t == 0) s0 = *(const f32x4*)sc;
;                         if (t <= 1) s1 = *(const f32x4*)(sc + 2816);
; #pragma unroll
;                         for (int j = 0; j < 4; ++j) {
;                             const float up1 = __shfl_up(a[j], 1, 16), up2 = __shfl_up(a[j], 2, 16);
;                             const float p1 = t == 0 ? s1[j] : up1, p2 = t == 0 ? s0[j] : (t == 1 ? s1[j] : up2);
;                             const float c = bb[j] + w0[j] * p2 + w1[j] * p1 + w2[j] * a[j];
;                             gg[j] = c * sigm(c) * uu[j];
;                         }
;                         *(u32x2*)(G + (size_t)row * 2816 + colt + 4 * n) = (u32x2){cvt_pk_bf16(gg[0], gg[1]), cvt_pk_bf16(gg[2], gg[3])};
;                         if (t >= 2) *(f32x4*)(ocs + (size_t)(bs * 2 + t - 2) * 2816 + colt + 4 * n) = a;
;                     }
	v_cndmask_b32_e64 v139, v138, v253, s[6:7]
	s_waitcnt lgkmcnt(2)
	v_cndmask_b32_e64 v138, v142, v252, s[6:7]
	s_waitcnt lgkmcnt(1)
	v_cndmask_b32_e64 v142, v143, v252, s[10:11]
	s_waitcnt lgkmcnt(0)
	v_cndmask_b32_e64 v143, v246, v253, s[10:11]
	v_cndmask_b32_e64 v143, v143, v249, s[6:7]
	v_cndmask_b32_e64 v142, v142, v248, s[6:7]
	v_pk_fma_f32 v[132:133], v[132:133], v[142:143], v[144:145]
	v_mul_f32_e32 v135, 0xbfb8aa3b, v131
	v_pk_fma_f32 v[132:133], v[136:137], v[138:139], v[132:133]
	v_exp_f32_e32 v134, v134
	v_pk_fma_f32 v[132:133], v[156:157], v[140:141], v[132:133]
	v_exp_f32_e32 v135, v135
	v_mul_f32_e32 v136, 0xbfb8aa3b, v132
	v_mul_f32_e32 v137, 0xbfb8aa3b, v133
	v_exp_f32_e32 v136, v136
	v_exp_f32_e32 v137, v137
	v_add_f32_e32 v134, 1.0, v134
	v_add_f32_e32 v135, 1.0, v135
	v_rcp_f32_e32 v134, v134
	v_rcp_f32_e32 v135, v135
	v_add_f32_e32 v136, 1.0, v136
	v_add_f32_e32 v137, 1.0, v137
	v_rcp_f32_e32 v136, v136
	v_rcp_f32_e32 v137, v137
	v_pk_mul_f32 v[130:131], v[130:131], v[134:135]
	v_pk_mul_f32 v[134:135], v[6:7], v[170:171] op_sel_hi:[1,0]
	v_pk_mul_f32 v[132:133], v[132:133], v[136:137]
	v_pk_mul_f32 v[130:131], v[134:135], v[130:131]
	v_pk_mul_f32 v[134:135], v[8:9], v[170:171] op_sel_hi:[1,0]
	v_cvt_pk_bf16_f32 v130, v130, v131
	v_pk_mul_f32 v[132:133], v[134:135], v[132:133]
	s_nop 0
	v_cvt_pk_bf16_f32 v131, v132, v133
	v_mov_b64_e32 v[132:133], s[42:43]
	v_mad_i64_i32 v[132:133], s[20:21], v187, s47, v[132:133]
	v_lshl_add_u64 v[228:229], v[168:169], 1, v[132:133]
	global_store_dwordx2 v[228:229], v[130:131], off
	s_and_saveexec_b64 s[88:89], s[8:9]
	s_cbranch_execz .LBB0_944
	v_lshl_add_u32 v132, v181, 1, v179
	v_mov_b64_e32 v[130:131], s[66:67]
	v_mad_i64_i32 v[130:131], s[20:21], v132, s48, v[130:131]
	v_lshl_add_u64 v[130:131], v[168:169], 2, v[130:131]
	global_store_dwordx4 v[130:131], v[154:157], off
.LBB0_944:
	s_or_b64 exec, exec, s[88:89]
	v_add_co_u32_e32 v134, vcc, 0x2000, v202
	global_load_dwordx4 v[130:133], v[202:203], off offset:16
	s_nop 0
	v_addc_co_u32_e32 v135, vcc, 0, v203, vcc
	v_add_co_u32_e32 v138, vcc, 0x5000, v202
	s_nop 0
	v_addc_co_u32_e32 v139, vcc, 0, v203, vcc
	global_load_dwordx4 v[134:137], v[134:135], off offset:3088
	s_nop 0
	global_load_dwordx4 v[138:141], v[138:139], off offset:2064
	s_nop 0
	global_load_dwordx4 v[142:145], v[206:207], off offset:16
	v_add_co_u32_e32 v250, vcc, 0x2000, v196
	s_nop 1
	v_addc_co_u32_e32 v251, vcc, 0, v197, vcc
	s_mov_b64 s[88:89], exec
	s_andn2_b64 exec, s[88:89], s[6:7]
	v_mov_b32_e32 v246, 0
	v_mov_b32_e32 v247, 0
	v_mov_b32_e32 v248, 0
	v_mov_b32_e32 v249, 0
	s_and_b64 exec, s[88:89], s[6:7]
	global_load_dwordx4 v[246:249], v[196:197], off offset:16
	s_andn2_b64 exec, s[88:89], s[12:13]
	v_mov_b32_e32 v250, 0
	v_mov_b32_e32 v251, 0
	v_mov_b32_e32 v252, 0
	v_mov_b32_e32 v253, 0
	s_and_b64 exec, s[88:89], s[12:13]
	global_load_dwordx4 v[250:253], v[250:251], off offset:3088
	s_mov_b64 exec, s[88:89]
	v_mov_b32_e32 v185, v184
	v_pk_mul_f32 v[154:155], v[122:123], v[184:185]
	ds_bpermute_b32 v156, v240, v155
	ds_bpermute_b32 v179, v240, v154
	ds_bpermute_b32 v181, v241, v154
	ds_bpermute_b32 v183, v241, v155
	s_waitcnt vmcnt(2) lgkmcnt(3)
	v_cndmask_b32_e64 v157, v156, v151, s[6:7]
	s_waitcnt lgkmcnt(2)
	v_cndmask_b32_e64 v156, v179, v150, s[6:7]
	s_waitcnt lgkmcnt(1)
	v_cndmask_b32_e64 v150, v181, v150, s[10:11]
	s_waitcnt lgkmcnt(0)
	v_cndmask_b32_e64 v151, v183, v151, s[10:11]
	v_cndmask_b32_e64 v147, v151, v147, s[6:7]
	v_cndmask_b32_e64 v146, v150, v146, s[6:7]
	v_pk_fma_f32 v[146:147], v[130:131], v[146:147], v[142:143]
	v_mov_b32_e32 v151, v184
	v_pk_fma_f32 v[146:147], v[134:135], v[156:157], v[146:147]
	s_nop 0
	v_pk_fma_f32 v[146:147], v[154:155], v[138:139], v[146:147]
	s_nop 0
	v_mul_f32_e32 v150, 0xbfb8aa3b, v146
	v_exp_f32_e32 v179, v150
	v_mov_b32_e32 v150, v184
	v_pk_mul_f32 v[156:157], v[124:125], v[150:151]
	ds_bpermute_b32 v181, v240, v157
	ds_bpermute_b32 v183, v240, v156
	ds_bpermute_b32 v185, v241, v156
	ds_bpermute_b32 v195, v241, v157
	v_add_f32_e32 v179, 1.0, v179
	s_waitcnt lgkmcnt(3)
	v_cndmask_b32_e64 v203, v181, v153, s[6:7]
	s_waitcnt lgkmcnt(2)
	v_cndmask_b32_e64 v202, v183, v152, s[6:7]
	s_waitcnt lgkmcnt(1)
	v_cndmask_b32_e64 v152, v185, v152, s[10:11]
	s_waitcnt lgkmcnt(0)
	v_cndmask_b32_e64 v153, v195, v153, s[10:11]
	v_cndmask_b32_e64 v149, v153, v149, s[6:7]
	v_cndmask_b32_e64 v148, v152, v148, s[6:7]
	v_pk_fma_f32 v[148:149], v[132:133], v[148:149], v[144:145]
	v_rcp_f32_e32 v194, v179
	v_pk_fma_f32 v[148:149], v[136:137], v[202:203], v[148:149]
	v_mul_f32_e32 v179, 0xbfb8aa3b, v147
	v_pk_fma_f32 v[148:149], v[156:157], v[140:141], v[148:149]
	v_exp_f32_e32 v179, v179
	v_mul_f32_e32 v152, 0xbfb8aa3b, v148
	v_mul_f32_e32 v153, 0xbfb8aa3b, v149
	v_exp_f32_e32 v152, v152
	v_exp_f32_e32 v153, v153
	v_add_f32_e32 v179, 1.0, v179
	v_rcp_f32_e32 v195, v179
	v_add_f32_e32 v152, 1.0, v152
	v_add_f32_e32 v153, 1.0, v153
	v_rcp_f32_e32 v152, v152
	v_rcp_f32_e32 v153, v153
	v_pk_mul_f32 v[146:147], v[146:147], v[194:195]
	v_pk_mul_f32 v[194:195], v[90:91], v[150:151]
	v_pk_mul_f32 v[150:151], v[92:93], v[150:151]
	v_pk_mul_f32 v[148:149], v[148:149], v[152:153]
	v_pk_mul_f32 v[146:147], v[194:195], v[146:147]
	v_pk_mul_f32 v[148:149], v[150:151], v[148:149]
	v_cvt_pk_bf16_f32 v146, v146, v147
	v_cvt_pk_bf16_f32 v147, v148, v149
	global_store_dwordx2 v[214:215], v[146:147], off offset:8
	s_and_saveexec_b64 s[88:89], s[8:9]
	s_cbranch_execz .LBB0_950
	v_mov_b64_e32 v[146:147], s[66:67]
	v_mad_i64_i32 v[146:147], s[20:21], v171, s48, v[146:147]
	v_lshl_add_u64 v[146:147], v[168:169], 2, v[146:147]
	global_store_dwordx4 v[146:147], v[154:157], off offset:16
; __device__ __forceinline__ unsigned cvt_pk_bf16(float lo, float hi) { f32x2_t v = {lo, hi}; bf16x2_t b = __builtin_convertvector(v, bf16x2_t); return __builtin_bit_cast(unsigned, b); }
; __device__ __forceinline__ float sigm(float x) { return __builtin_amdgcn_rcpf(1.0f + __builtin_amdgcn_exp2f(-x * LOG2E)); }
;     __device__ __forceinline__ void operator()(const f32x4 (&acc)[2][2][4][2], const Unit& u, int wr, int wc, int fr, int fq) const {
;     ...
;                         const int row = row0 + ai * HALF + m * 16, rl = row - MPR, bs = rl >> 2, t = rl & 3;
;                         const f32x4 a = acc[ai][0][m][n] * rs[ai][m], uu = acc[ai][1][m][n] * rs[ai][m]; f32x4 gg, s0 = {0.f, 0.f, 0.f, 0.f}, s1 = {0.f, 0.f, 0.f, 0.f};
;                         const float* sc = sconv + (size_t)bs * 2 * 2816 + colt + 4 * n;
;                         if (t == 0) s0 = *(const f32x4*)sc;
;                         if (t <= 1) s1 = *(const f32x4*)(sc + 2816);
; #pragma unroll
;                         for (int j = 0; j < 4; ++j) {
;                             const float up1 = __shfl_up(a[j], 1, 16), up2 = __shfl_up(a[j], 2, 16);
;                             const float p1 = t == 0 ? s1[j] : up1, p2 = t == 0 ? s0[j] : (t == 1 ? s1[j] : up2);
;                             const float c = bb[j] + w0[j] * p2 + w1[j] * p1 + w2[j] * a[j];
;                             gg[j] = c * sigm(c) * uu[j];
;                         }
;                         *(u32x2*)(G + (size_t)row * 2816 + colt + 4 * n) = (u32x2){cvt_pk_bf16(gg[0], gg[1]), cvt_pk_bf16(gg[2], gg[3])};
;                         if (t >= 2) *(f32x4*)(ocs + (size_t)(bs * 2 + t - 2) * 2816 + colt + 4 * n) = a;
.LBB0_950:
	s_or_b64 exec, exec, s[88:89]
	v_add_co_u32_e32 v150, vcc, 0x2000, v198
	s_nop 1
	v_addc_co_u32_e32 v151, vcc, 0, v199, vcc
	s_mov_b64 s[88:89], exec
	s_andn2_b64 exec, s[88:89], s[6:7]
	v_mov_b32_e32 v146, 0
	v_mov_b32_e32 v147, 0
	v_mov_b32_e32 v148, 0
	v_mov_b32_e32 v149, 0
	s_and_b64 exec, s[88:89], s[6:7]
	global_load_dwordx4 v[146:149], v[198:199], off offset:16
	s_andn2_b64 exec, s[88:89], s[12:13]
	v_mov_b32_e32 v150, 0
	v_mov_b32_e32 v151, 0
	v_mov_b32_e32 v152, 0
	v_mov_b32_e32 v153, 0
	s_and_b64 exec, s[88:89], s[12:13]
	global_load_dwordx4 v[150:153], v[150:151], off offset:3088
	s_mov_b64 exec, s[88:89]
	v_mov_b32_e32 v183, v182
	v_pk_mul_f32 v[154:155], v[114:115], v[182:183]
	ds_bpermute_b32 v156, v240, v155
	ds_bpermute_b32 v171, v240, v154
	ds_bpermute_b32 v179, v241, v154
	ds_bpermute_b32 v181, v241, v155
	s_waitcnt vmcnt(4) lgkmcnt(3)
	v_cndmask_b32_e64 v157, v156, v251, s[6:7]
	s_waitcnt lgkmcnt(2)
	v_cndmask_b32_e64 v156, v171, v250, s[6:7]
	s_waitcnt lgkmcnt(1)
	v_cndmask_b32_e64 v250, v179, v250, s[10:11]
	s_waitcnt lgkmcnt(0)
	v_cndmask_b32_e64 v251, v181, v251, s[10:11]
	v_cndmask_b32_e64 v247, v251, v247, s[6:7]
	v_cndmask_b32_e64 v246, v250, v246, s[6:7]
	v_pk_fma_f32 v[246:247], v[130:131], v[246:247], v[142:143]
	v_mov_b32_e32 v251, v182
	v_pk_fma_f32 v[246:247], v[134:135], v[156:157], v[246:247]
	s_nop 0
	v_pk_fma_f32 v[246:247], v[154:155], v[138:139], v[246:247]
	s_nop 0
	v_mul_f32_e32 v250, 0xbfb8aa3b, v246
	v_exp_f32_e32 v171, v250
	v_mov_b32_e32 v250, v182
	v_pk_mul_f32 v[156:157], v[116:117], v[250:251]
	ds_bpermute_b32 v179, v240, v157
	ds_bpermute_b32 v181, v240, v156
	ds_bpermute_b32 v183, v241, v156
	ds_bpermute_b32 v185, v241, v157
	v_add_f32_e32 v171, 1.0, v171
	s_waitcnt lgkmcnt(3)
	v_cndmask_b32_e64 v197, v179, v253, s[6:7]
	s_waitcnt lgkmcnt(2)
	v_cndmask_b32_e64 v196, v181, v252, s[6:7]
	s_waitcnt lgkmcnt(1)
	v_cndmask_b32_e64 v252, v183, v252, s[10:11]
	s_waitcnt lgkmcnt(0)
	v_cndmask_b32_e64 v253, v185, v253, s[10:11]
	v_cndmask_b32_e64 v249, v253, v249, s[6:7]
	v_cndmask_b32_e64 v248, v252, v248, s[6:7]
	v_pk_fma_f32 v[248:249], v[132:133], v[248:249], v[144:145]
	v_rcp_f32_e32 v194, v171
	v_pk_fma_f32 v[248:249], v[136:137], v[196:197], v[248:249]
	v_mul_f32_e32 v171, 0xbfb8aa3b, v247
	v_pk_fma_f32 v[248:249], v[156:157], v[140:141], v[248:249]
	v_exp_f32_e32 v171, v171
	v_mul_f32_e32 v252, 0xbfb8aa3b, v248
	v_mul_f32_e32 v253, 0xbfb8aa3b, v249
	v_exp_f32_e32 v252, v252
	v_exp_f32_e32 v253, v253
	v_add_f32_e32 v171, 1.0, v171
	v_rcp_f32_e32 v195, v171
	v_add_f32_e32 v252, 1.0, v252
	v_add_f32_e32 v253, 1.0, v253
	v_rcp_f32_e32 v252, v252
	v_rcp_f32_e32 v253, v253
	v_pk_mul_f32 v[246:247], v[246:247], v[194:195]
	v_pk_mul_f32 v[194:195], v[82:83], v[250:251]
	v_pk_mul_f32 v[250:251], v[84:85], v[250:251]
	v_pk_mul_f32 v[248:249], v[248:249], v[252:253]
	v_pk_mul_f32 v[246:247], v[194:195], v[246:247]
	v_pk_mul_f32 v[248:249], v[250:251], v[248:249]
	v_cvt_pk_bf16_f32 v246, v246, v247
	v_cvt_pk_bf16_f32 v247, v248, v249
	global_store_dwordx2 v[216:217], v[246:247], off offset:8
	s_and_saveexec_b64 s[88:89], s[8:9]
	s_cbranch_execz .LBB0_956
	v_mov_b64_e32 v[246:247], s[66:67]
	v_mad_i64_i32 v[246:247], s[20:21], v173, s48, v[246:247]
	v_lshl_add_u64 v[246:247], v[168:169], 2, v[246:247]
	global_store_dwordx4 v[246:247], v[154:157], off offset:16
.LBB0_956:
	s_or_b64 exec, exec, s[88:89]
	v_add_co_u32_e32 v250, vcc, 0x2000, v200
	s_nop 1
	v_addc_co_u32_e32 v251, vcc, 0, v201, vcc
	s_mov_b64 s[88:89], exec
	s_andn2_b64 exec, s[88:89], s[6:7]
	v_mov_b32_e32 v246, 0
	v_mov_b32_e32 v247, 0
	v_mov_b32_e32 v248, 0
	v_mov_b32_e32 v249, 0
	s_and_b64 exec, s[88:89], s[6:7]
	global_load_dwordx4 v[246:249], v[200:201], off offset:16
	s_andn2_b64 exec, s[88:89], s[12:13]
	v_mov_b32_e32 v250, 0
	v_mov_b32_e32 v251, 0
	v_mov_b32_e32 v252, 0
	v_mov_b32_e32 v253, 0
	s_and_b64 exec, s[88:89], s[12:13]
	global_load_dwordx4 v[250:253], v[250:251], off offset:3088
	s_mov_b64 exec, s[88:89]
	v_mov_b32_e32 v181, v180
	v_pk_mul_f32 v[154:155], v[106:107], v[180:181]
	ds_bpermute_b32 v156, v240, v155
	ds_bpermute_b32 v171, v240, v154
	ds_bpermute_b32 v173, v241, v154
	ds_bpermute_b32 v179, v241, v155
	s_waitcnt vmcnt(4) lgkmcnt(3)
	v_cndmask_b32_e64 v157, v156, v151, s[6:7]
	s_waitcnt lgkmcnt(2)
	v_cndmask_b32_e64 v156, v171, v150, s[6:7]
	s_waitcnt lgkmcnt(1)
	v_cndmask_b32_e64 v150, v173, v150, s[10:11]
	s_waitcnt lgkmcnt(0)
	v_cndmask_b32_e64 v151, v179, v151, s[10:11]
	v_cndmask_b32_e64 v147, v151, v147, s[6:7]
	v_cndmask_b32_e64 v146, v150, v146, s[6:7]
	v_pk_fma_f32 v[146:147], v[130:131], v[146:147], v[142:143]
	v_mov_b32_e32 v151, v180
	v_pk_fma_f32 v[146:147], v[134:135], v[156:157], v[146:147]
	s_nop 0
	v_pk_fma_f32 v[146:147], v[154:155], v[138:139], v[146:147]
	s_nop 0
	v_mul_f32_e32 v150, 0xbfb8aa3b, v146
	v_exp_f32_e32 v171, v150
	v_mov_b32_e32 v150, v180
	v_pk_mul_f32 v[156:157], v[108:109], v[150:151]
	ds_bpermute_b32 v173, v240, v157
	ds_bpermute_b32 v179, v240, v156
	ds_bpermute_b32 v181, v241, v156
	ds_bpermute_b32 v183, v241, v157
	v_add_f32_e32 v171, 1.0, v171
	s_waitcnt lgkmcnt(3)
	v_cndmask_b32_e64 v197, v173, v153, s[6:7]
	s_waitcnt lgkmcnt(2)
	v_cndmask_b32_e64 v196, v179, v152, s[6:7]
	s_waitcnt lgkmcnt(1)
	v_cndmask_b32_e64 v152, v181, v152, s[10:11]
	s_waitcnt lgkmcnt(0)
	v_cndmask_b32_e64 v153, v183, v153, s[10:11]
	v_cndmask_b32_e64 v149, v153, v149, s[6:7]
	v_cndmask_b32_e64 v148, v152, v148, s[6:7]
	v_pk_fma_f32 v[148:149], v[132:133], v[148:149], v[144:145]
	v_rcp_f32_e32 v194, v171
	v_pk_fma_f32 v[148:149], v[136:137], v[196:197], v[148:149]
	v_mul_f32_e32 v171, 0xbfb8aa3b, v147
	v_pk_fma_f32 v[148:149], v[156:157], v[140:141], v[148:149]
	v_exp_f32_e32 v171, v171
	v_mul_f32_e32 v152, 0xbfb8aa3b, v148
	v_mul_f32_e32 v153, 0xbfb8aa3b, v149
	v_exp_f32_e32 v152, v152
	v_exp_f32_e32 v153, v153
	v_add_f32_e32 v171, 1.0, v171
	v_rcp_f32_e32 v195, v171
	v_add_f32_e32 v152, 1.0, v152
	v_add_f32_e32 v153, 1.0, v153
	v_rcp_f32_e32 v152, v152
	v_rcp_f32_e32 v153, v153
	v_pk_mul_f32 v[146:147], v[146:147], v[194:195]
	v_pk_mul_f32 v[194:195], v[74:75], v[150:151]
	v_pk_mul_f32 v[150:151], v[76:77], v[150:151]
	v_pk_mul_f32 v[148:149], v[148:149], v[152:153]
	v_pk_mul_f32 v[146:147], v[194:195], v[146:147]
	v_pk_mul_f32 v[148:149], v[150:151], v[148:149]
	v_cvt_pk_bf16_f32 v146, v146, v147
	v_cvt_pk_bf16_f32 v147, v148, v149
	global_store_dwordx2 v[218:219], v[146:147], off offset:8
	s_and_saveexec_b64 s[88:89], s[8:9]
	s_cbranch_execz .LBB0_962
	v_mov_b64_e32 v[146:147], s[66:67]
	v_mad_i64_i32 v[146:147], s[20:21], v175, s48, v[146:147]
	v_lshl_add_u64 v[146:147], v[168:169], 2, v[146:147]
	global_store_dwordx4 v[146:147], v[154:157], off offset:16
; __device__ __forceinline__ unsigned cvt_pk_bf16(float lo, float hi) { f32x2_t v = {lo, hi}; bf16x2_t b = __builtin_convertvector(v, bf16x2_t); return __builtin_bit_cast(unsigned, b); }
; __device__ __forceinline__ float sigm(float x) { return __builtin_amdgcn_rcpf(1.0f + __builtin_amdgcn_exp2f(-x * LOG2E)); }
;     __device__ __forceinline__ void operator()(const f32x4 (&acc)[2][2][4][2], const Unit& u, int wr, int wc, int fr, int fq) const {
;     ...
;                         const int row = row0 + ai * HALF + m * 16, rl = row - MPR, bs = rl >> 2, t = rl & 3;
;                         const f32x4 a = acc[ai][0][m][n] * rs[ai][m], uu = acc[ai][1][m][n] * rs[ai][m]; f32x4 gg, s0 = {0.f, 0.f, 0.f, 0.f}, s1 = {0.f, 0.f, 0.f, 0.f};
;                         const float* sc = sconv + (size_t)bs * 2 * 2816 + colt + 4 * n;
;                         if (t == 0) s0 = *(const f32x4*)sc;
;                         if (t <= 1) s1 = *(const f32x4*)(sc + 2816);
; #pragma unroll
;                         for (int j = 0; j < 4; ++j) {
;                             const float up1 = __shfl_up(a[j], 1, 16), up2 = __shfl_up(a[j], 2, 16);
;                             const float p1 = t == 0 ? s1[j] : up1, p2 = t == 0 ? s0[j] : (t == 1 ? s1[j] : up2);
;                             const float c = bb[j] + w0[j] * p2 + w1[j] * p1 + w2[j] * a[j];
;                             gg[j] = c * sigm(c) * uu[j];
;                         }
;                         *(u32x2*)(G + (size_t)row * 2816 + colt + 4 * n) = (u32x2){cvt_pk_bf16(gg[0], gg[1]), cvt_pk_bf16(gg[2], gg[3])};
;                         if (t >= 2) *(f32x4*)(ocs + (size_t)(bs * 2 + t - 2) * 2816 + colt + 4 * n) = a;
.LBB0_962:
	s_or_b64 exec, exec, s[88:89]
	v_add_co_u32_e32 v150, vcc, 0x2000, v204
	s_nop 1
	v_addc_co_u32_e32 v151, vcc, 0, v205, vcc
	s_mov_b64 s[88:89], exec
	s_andn2_b64 exec, s[88:89], s[6:7]
	v_mov_b32_e32 v146, 0
	v_mov_b32_e32 v147, 0
	v_mov_b32_e32 v148, 0
	v_mov_b32_e32 v149, 0
	s_and_b64 exec, s[88:89], s[6:7]
	global_load_dwordx4 v[146:149], v[204:205], off offset:16
	s_andn2_b64 exec, s[88:89], s[12:13]
	v_mov_b32_e32 v150, 0
	v_mov_b32_e32 v151, 0
	v_mov_b32_e32 v152, 0
	v_mov_b32_e32 v153, 0
	s_and_b64 exec, s[88:89], s[12:13]
	global_load_dwordx4 v[150:153], v[150:151], off offset:3088
	s_mov_b64 exec, s[88:89]
	v_mov_b32_e32 v179, v178
	v_pk_mul_f32 v[154:155], v[98:99], v[178:179]
	ds_bpermute_b32 v156, v240, v155
	ds_bpermute_b32 v171, v240, v154
	ds_bpermute_b32 v173, v241, v154
	ds_bpermute_b32 v175, v241, v155
	s_waitcnt vmcnt(4) lgkmcnt(3)
	v_cndmask_b32_e64 v157, v156, v251, s[6:7]
	s_waitcnt lgkmcnt(2)
	v_cndmask_b32_e64 v156, v171, v250, s[6:7]
	s_waitcnt lgkmcnt(1)
	v_cndmask_b32_e64 v250, v173, v250, s[10:11]
	s_waitcnt lgkmcnt(0)
	v_cndmask_b32_e64 v251, v175, v251, s[10:11]
	v_cndmask_b32_e64 v247, v251, v247, s[6:7]
	v_cndmask_b32_e64 v246, v250, v246, s[6:7]
	v_pk_fma_f32 v[246:247], v[130:131], v[246:247], v[142:143]
	v_mov_b32_e32 v251, v178
	v_pk_fma_f32 v[246:247], v[134:135], v[156:157], v[246:247]
	s_nop 0
	v_pk_fma_f32 v[246:247], v[154:155], v[138:139], v[246:247]
	s_nop 0
	v_mul_f32_e32 v250, 0xbfb8aa3b, v246
	v_exp_f32_e32 v171, v250
	v_mov_b32_e32 v250, v178
	v_pk_mul_f32 v[156:157], v[100:101], v[250:251]
	ds_bpermute_b32 v173, v240, v157
	ds_bpermute_b32 v175, v240, v156
	ds_bpermute_b32 v179, v241, v156
	ds_bpermute_b32 v181, v241, v157
	v_add_f32_e32 v171, 1.0, v171
	s_waitcnt lgkmcnt(3)
	v_cndmask_b32_e64 v197, v173, v253, s[6:7]
	s_waitcnt lgkmcnt(2)
	v_cndmask_b32_e64 v196, v175, v252, s[6:7]
	s_waitcnt lgkmcnt(1)
	v_cndmask_b32_e64 v252, v179, v252, s[10:11]
	s_waitcnt lgkmcnt(0)
	v_cndmask_b32_e64 v253, v181, v253, s[10:11]
	v_cndmask_b32_e64 v249, v253, v249, s[6:7]
	v_cndmask_b32_e64 v248, v252, v248, s[6:7]
	v_pk_fma_f32 v[248:249], v[132:133], v[248:249], v[144:145]
	v_rcp_f32_e32 v194, v171
	v_pk_fma_f32 v[248:249], v[136:137], v[196:197], v[248:249]
	v_mul_f32_e32 v171, 0xbfb8aa3b, v247
	v_pk_fma_f32 v[248:249], v[156:157], v[140:141], v[248:249]
	v_exp_f32_e32 v171, v171
	v_mul_f32_e32 v252, 0xbfb8aa3b, v248
	v_mul_f32_e32 v253, 0xbfb8aa3b, v249
	v_exp_f32_e32 v252, v252
	v_exp_f32_e32 v253, v253
	v_add_f32_e32 v171, 1.0, v171
	v_rcp_f32_e32 v195, v171
	v_add_f32_e32 v252, 1.0, v252
	v_add_f32_e32 v253, 1.0, v253
	v_rcp_f32_e32 v252, v252
	v_rcp_f32_e32 v253, v253
	v_pk_mul_f32 v[246:247], v[246:247], v[194:195]
	v_pk_mul_f32 v[194:195], v[66:67], v[250:251]
	v_pk_mul_f32 v[250:251], v[68:69], v[250:251]
	v_pk_mul_f32 v[248:249], v[248:249], v[252:253]
	v_pk_mul_f32 v[246:247], v[194:195], v[246:247]
	v_pk_mul_f32 v[248:249], v[250:251], v[248:249]
	v_cvt_pk_bf16_f32 v246, v246, v247
	v_cvt_pk_bf16_f32 v247, v248, v249
	global_store_dwordx2 v[220:221], v[246:247], off offset:8
	s_and_saveexec_b64 s[88:89], s[8:9]
	s_cbranch_execz .LBB0_968
	v_mov_b64_e32 v[246:247], s[66:67]
	v_mad_i64_i32 v[246:247], s[20:21], v177, s48, v[246:247]
	v_lshl_add_u64 v[246:247], v[168:169], 2, v[246:247]
	global_store_dwordx4 v[246:247], v[154:157], off offset:16
.LBB0_968:
	s_or_b64 exec, exec, s[88:89]
	v_add_co_u32_e32 v250, vcc, 0x2000, v208
	s_nop 1
	v_addc_co_u32_e32 v251, vcc, 0, v209, vcc
	s_mov_b64 s[88:89], exec
	s_andn2_b64 exec, s[88:89], s[6:7]
	v_mov_b32_e32 v246, 0
	v_mov_b32_e32 v247, 0
	v_mov_b32_e32 v248, 0
	v_mov_b32_e32 v249, 0
	s_and_b64 exec, s[88:89], s[6:7]
	global_load_dwordx4 v[246:249], v[208:209], off offset:16
	s_andn2_b64 exec, s[88:89], s[12:13]
	v_mov_b32_e32 v250, 0
	v_mov_b32_e32 v251, 0
	v_mov_b32_e32 v252, 0
	v_mov_b32_e32 v253, 0
	s_and_b64 exec, s[88:89], s[12:13]
	global_load_dwordx4 v[250:253], v[250:251], off offset:3088
	s_mov_b64 exec, s[88:89]
	v_mov_b32_e32 v177, v176
	v_pk_mul_f32 v[154:155], v[58:59], v[176:177]
	ds_bpermute_b32 v156, v240, v155
	ds_bpermute_b32 v171, v240, v154
	ds_bpermute_b32 v173, v241, v154
	ds_bpermute_b32 v175, v241, v155
	s_waitcnt vmcnt(4) lgkmcnt(3)
	v_cndmask_b32_e64 v157, v156, v151, s[6:7]
	s_waitcnt lgkmcnt(2)
	v_cndmask_b32_e64 v156, v171, v150, s[6:7]
	s_waitcnt lgkmcnt(1)
	v_cndmask_b32_e64 v150, v173, v150, s[10:11]
	s_waitcnt lgkmcnt(0)
	v_cndmask_b32_e64 v151, v175, v151, s[10:11]
	v_cndmask_b32_e64 v147, v151, v147, s[6:7]
	v_cndmask_b32_e64 v146, v150, v146, s[6:7]
	v_pk_fma_f32 v[146:147], v[130:131], v[146:147], v[142:143]
	v_mov_b32_e32 v151, v176
	v_pk_fma_f32 v[146:147], v[134:135], v[156:157], v[146:147]
	s_nop 0
	v_pk_fma_f32 v[146:147], v[154:155], v[138:139], v[146:147]
	s_nop 0
	v_mul_f32_e32 v150, 0xbfb8aa3b, v146
	v_exp_f32_e32 v171, v150
	v_mov_b32_e32 v150, v176
	v_pk_mul_f32 v[156:157], v[60:61], v[150:151]
	ds_bpermute_b32 v173, v240, v157
	ds_bpermute_b32 v175, v240, v156
	ds_bpermute_b32 v177, v241, v156
	ds_bpermute_b32 v179, v241, v157
	v_add_f32_e32 v171, 1.0, v171
	s_waitcnt lgkmcnt(3)
	v_cndmask_b32_e64 v197, v173, v153, s[6:7]
	s_waitcnt lgkmcnt(2)
	v_cndmask_b32_e64 v196, v175, v152, s[6:7]
	s_waitcnt lgkmcnt(1)
	v_cndmask_b32_e64 v152, v177, v152, s[10:11]
	s_waitcnt lgkmcnt(0)
	v_cndmask_b32_e64 v153, v179, v153, s[10:11]
	v_cndmask_b32_e64 v149, v153, v149, s[6:7]
	v_cndmask_b32_e64 v148, v152, v148, s[6:7]
	v_pk_fma_f32 v[148:149], v[132:133], v[148:149], v[144:145]
	v_rcp_f32_e32 v194, v171
	v_pk_fma_f32 v[148:149], v[136:137], v[196:197], v[148:149]
	v_mul_f32_e32 v171, 0xbfb8aa3b, v147
	v_pk_fma_f32 v[148:149], v[156:157], v[140:141], v[148:149]
	v_exp_f32_e32 v171, v171
	v_mul_f32_e32 v152, 0xbfb8aa3b, v148
	v_mul_f32_e32 v153, 0xbfb8aa3b, v149
	v_exp_f32_e32 v152, v152
	v_exp_f32_e32 v153, v153
	v_add_f32_e32 v171, 1.0, v171
	v_rcp_f32_e32 v195, v171
	v_add_f32_e32 v152, 1.0, v152
	v_add_f32_e32 v153, 1.0, v153
	v_rcp_f32_e32 v152, v152
	v_rcp_f32_e32 v153, v153
	v_pk_mul_f32 v[146:147], v[146:147], v[194:195]
	v_pk_mul_f32 v[194:195], v[26:27], v[150:151]
	v_pk_mul_f32 v[150:151], v[28:29], v[150:151]
	v_pk_mul_f32 v[148:149], v[148:149], v[152:153]
	v_pk_mul_f32 v[146:147], v[194:195], v[146:147]
	v_pk_mul_f32 v[148:149], v[150:151], v[148:149]
	v_cvt_pk_bf16_f32 v146, v146, v147
	v_cvt_pk_bf16_f32 v147, v148, v149
	global_store_dwordx2 v[222:223], v[146:147], off offset:8
	s_and_saveexec_b64 s[88:89], s[8:9]
	s_cbranch_execz .LBB0_974
	v_mov_b64_e32 v[146:147], s[66:67]
	v_mad_i64_i32 v[146:147], s[20:21], v243, s48, v[146:147]
	v_lshl_add_u64 v[146:147], v[168:169], 2, v[146:147]
	global_store_dwordx4 v[146:147], v[154:157], off offset:16
; __device__ __forceinline__ unsigned cvt_pk_bf16(float lo, float hi) { f32x2_t v = {lo, hi}; bf16x2_t b = __builtin_convertvector(v, bf16x2_t); return __builtin_bit_cast(unsigned, b); }
; __device__ __forceinline__ float sigm(float x) { return __builtin_amdgcn_rcpf(1.0f + __builtin_amdgcn_exp2f(-x * LOG2E)); }
;     __device__ __forceinline__ void operator()(const f32x4 (&acc)[2][2][4][2], const Unit& u, int wr, int wc, int fr, int fq) const {
;     ...
;                         const int row = row0 + ai * HALF + m * 16, rl = row - MPR, bs = rl >> 2, t = rl & 3;
;                         const f32x4 a = acc[ai][0][m][n] * rs[ai][m], uu = acc[ai][1][m][n] * rs[ai][m]; f32x4 gg, s0 = {0.f, 0.f, 0.f, 0.f}, s1 = {0.f, 0.f, 0.f, 0.f};
;                         const float* sc = sconv + (size_t)bs * 2 * 2816 + colt + 4 * n;
;                         if (t == 0) s0 = *(const f32x4*)sc;
;                         if (t <= 1) s1 = *(const f32x4*)(sc + 2816);
; #pragma unroll
;                         for (int j = 0; j < 4; ++j) {
;                             const float up1 = __shfl_up(a[j], 1, 16), up2 = __shfl_up(a[j], 2, 16);
;                             const float p1 = t == 0 ? s1[j] : up1, p2 = t == 0 ? s0[j] : (t == 1 ? s1[j] : up2);
;                             const float c = bb[j] + w0[j] * p2 + w1[j] * p1 + w2[j] * a[j];
;                             gg[j] = c * sigm(c) * uu[j];
;                         }
;                         *(u32x2*)(G + (size_t)row * 2816 + colt + 4 * n) = (u32x2){cvt_pk_bf16(gg[0], gg[1]), cvt_pk_bf16(gg[2], gg[3])};
;                         if (t >= 2) *(f32x4*)(ocs + (size_t)(bs * 2 + t - 2) * 2816 + colt + 4 * n) = a;
.LBB0_974:
	s_or_b64 exec, exec, s[88:89]
	v_add_co_u32_e32 v150, vcc, 0x2000, v210
	s_nop 1
	v_addc_co_u32_e32 v151, vcc, 0, v211, vcc
	s_mov_b64 s[88:89], exec
	s_andn2_b64 exec, s[88:89], s[6:7]
	v_mov_b32_e32 v146, 0
	v_mov_b32_e32 v147, 0
	v_mov_b32_e32 v148, 0
	v_mov_b32_e32 v149, 0
	s_and_b64 exec, s[88:89], s[6:7]
	global_load_dwordx4 v[146:149], v[210:211], off offset:16
	s_andn2_b64 exec, s[88:89], s[12:13]
	v_mov_b32_e32 v150, 0
	v_mov_b32_e32 v151, 0
	v_mov_b32_e32 v152, 0
	v_mov_b32_e32 v153, 0
	s_and_b64 exec, s[88:89], s[12:13]
	global_load_dwordx4 v[150:153], v[150:151], off offset:3088
	s_mov_b64 exec, s[88:89]
	v_mov_b32_e32 v175, v174
	v_pk_mul_f32 v[154:155], v[50:51], v[174:175]
	ds_bpermute_b32 v156, v240, v155
	ds_bpermute_b32 v171, v240, v154
	ds_bpermute_b32 v173, v241, v154
	ds_bpermute_b32 v175, v241, v155
	s_waitcnt vmcnt(4) lgkmcnt(3)
	v_cndmask_b32_e64 v157, v156, v251, s[6:7]
	s_waitcnt lgkmcnt(2)
	v_cndmask_b32_e64 v156, v171, v250, s[6:7]
	s_waitcnt lgkmcnt(1)
	v_cndmask_b32_e64 v250, v173, v250, s[10:11]
	s_waitcnt lgkmcnt(0)
	v_cndmask_b32_e64 v251, v175, v251, s[10:11]
	v_cndmask_b32_e64 v247, v251, v247, s[6:7]
	v_cndmask_b32_e64 v246, v250, v246, s[6:7]
	v_pk_fma_f32 v[246:247], v[130:131], v[246:247], v[142:143]
	v_mov_b32_e32 v251, v174
	v_pk_fma_f32 v[246:247], v[134:135], v[156:157], v[246:247]
	s_nop 0
	v_pk_fma_f32 v[246:247], v[154:155], v[138:139], v[246:247]
	s_nop 0
	v_mul_f32_e32 v250, 0xbfb8aa3b, v246
	v_exp_f32_e32 v171, v250
	v_mov_b32_e32 v250, v174
	v_pk_mul_f32 v[156:157], v[52:53], v[250:251]
	ds_bpermute_b32 v173, v240, v157
	ds_bpermute_b32 v175, v240, v156
	ds_bpermute_b32 v177, v241, v156
	ds_bpermute_b32 v179, v241, v157
	v_add_f32_e32 v171, 1.0, v171
	s_waitcnt lgkmcnt(3)
	v_cndmask_b32_e64 v197, v173, v253, s[6:7]
	s_waitcnt lgkmcnt(2)
	v_cndmask_b32_e64 v196, v175, v252, s[6:7]
	s_waitcnt lgkmcnt(1)
	v_cndmask_b32_e64 v252, v177, v252, s[10:11]
	s_waitcnt lgkmcnt(0)
	v_cndmask_b32_e64 v253, v179, v253, s[10:11]
	v_cndmask_b32_e64 v249, v253, v249, s[6:7]
	v_cndmask_b32_e64 v248, v252, v248, s[6:7]
	v_pk_fma_f32 v[248:249], v[132:133], v[248:249], v[144:145]
	v_rcp_f32_e32 v194, v171
	v_pk_fma_f32 v[248:249], v[136:137], v[196:197], v[248:249]
	v_mul_f32_e32 v171, 0xbfb8aa3b, v247
	v_pk_fma_f32 v[248:249], v[156:157], v[140:141], v[248:249]
	v_exp_f32_e32 v171, v171
	v_mul_f32_e32 v252, 0xbfb8aa3b, v248
	v_mul_f32_e32 v253, 0xbfb8aa3b, v249
	v_exp_f32_e32 v252, v252
	v_exp_f32_e32 v253, v253
	v_add_f32_e32 v171, 1.0, v171
	v_rcp_f32_e32 v195, v171
	v_add_f32_e32 v252, 1.0, v252
	v_add_f32_e32 v253, 1.0, v253
	v_rcp_f32_e32 v252, v252
	v_rcp_f32_e32 v253, v253
	v_pk_mul_f32 v[246:247], v[246:247], v[194:195]
	v_pk_mul_f32 v[194:195], v[18:19], v[250:251]
	v_pk_mul_f32 v[250:251], v[20:21], v[250:251]
	v_pk_mul_f32 v[248:249], v[248:249], v[252:253]
	v_pk_mul_f32 v[246:247], v[194:195], v[246:247]
	v_pk_mul_f32 v[248:249], v[250:251], v[248:249]
	v_cvt_pk_bf16_f32 v246, v246, v247
	v_cvt_pk_bf16_f32 v247, v248, v249
	global_store_dwordx2 v[224:225], v[246:247], off offset:8
	s_and_saveexec_b64 s[88:89], s[8:9]
	s_cbranch_execz .LBB0_980
	v_mov_b64_e32 v[246:247], s[66:67]
	v_mad_i64_i32 v[246:247], s[20:21], v244, s48, v[246:247]
	v_lshl_add_u64 v[246:247], v[168:169], 2, v[246:247]
	global_store_dwordx4 v[246:247], v[154:157], off offset:16
.LBB0_980:
	s_or_b64 exec, exec, s[88:89]
	v_mov_b32_e32 v173, v172
	v_pk_mul_f32 v[154:155], v[42:43], v[172:173]
	ds_bpermute_b32 v156, v240, v155
	ds_bpermute_b32 v171, v240, v154
	ds_bpermute_b32 v173, v241, v154
	ds_bpermute_b32 v175, v241, v155
	s_waitcnt vmcnt(2) lgkmcnt(3)
	v_cndmask_b32_e64 v157, v156, v151, s[6:7]
	s_waitcnt lgkmcnt(2)
	v_cndmask_b32_e64 v156, v171, v150, s[6:7]
	s_waitcnt lgkmcnt(1)
	v_cndmask_b32_e64 v150, v173, v150, s[10:11]
	s_waitcnt lgkmcnt(0)
	v_cndmask_b32_e64 v151, v175, v151, s[10:11]
	v_cndmask_b32_e64 v147, v151, v147, s[6:7]
	v_cndmask_b32_e64 v146, v150, v146, s[6:7]
	v_pk_fma_f32 v[146:147], v[130:131], v[146:147], v[142:143]
	v_mov_b32_e32 v151, v172
	v_pk_fma_f32 v[146:147], v[134:135], v[156:157], v[146:147]
	s_nop 0
	v_pk_fma_f32 v[146:147], v[154:155], v[138:139], v[146:147]
	s_nop 0
	v_mul_f32_e32 v150, 0xbfb8aa3b, v146
	v_exp_f32_e32 v171, v150
	v_mov_b32_e32 v150, v172
	v_pk_mul_f32 v[156:157], v[44:45], v[150:151]
	ds_bpermute_b32 v173, v240, v157
	ds_bpermute_b32 v175, v240, v156
	ds_bpermute_b32 v177, v241, v156
	ds_bpermute_b32 v179, v241, v157
	v_add_f32_e32 v171, 1.0, v171
	s_waitcnt lgkmcnt(3)
	v_cndmask_b32_e64 v197, v173, v153, s[6:7]
	s_waitcnt lgkmcnt(2)
	v_cndmask_b32_e64 v196, v175, v152, s[6:7]
	s_waitcnt lgkmcnt(1)
	v_cndmask_b32_e64 v152, v177, v152, s[10:11]
	s_waitcnt lgkmcnt(0)
	v_cndmask_b32_e64 v153, v179, v153, s[10:11]
	v_cndmask_b32_e64 v149, v153, v149, s[6:7]
	v_cndmask_b32_e64 v148, v152, v148, s[6:7]
	v_pk_fma_f32 v[148:149], v[132:133], v[148:149], v[144:145]
	v_rcp_f32_e32 v194, v171
	v_pk_fma_f32 v[148:149], v[136:137], v[196:197], v[148:149]
	v_mul_f32_e32 v171, 0xbfb8aa3b, v147
	v_pk_fma_f32 v[148:149], v[156:157], v[140:141], v[148:149]
	v_exp_f32_e32 v171, v171
	v_mul_f32_e32 v152, 0xbfb8aa3b, v148
	v_mul_f32_e32 v153, 0xbfb8aa3b, v149
	v_exp_f32_e32 v152, v152
	v_exp_f32_e32 v153, v153
	v_add_f32_e32 v171, 1.0, v171
	v_rcp_f32_e32 v195, v171
	v_add_f32_e32 v152, 1.0, v152
	v_add_f32_e32 v153, 1.0, v153
	v_rcp_f32_e32 v152, v152
	v_rcp_f32_e32 v153, v153
	v_pk_mul_f32 v[146:147], v[146:147], v[194:195]
	v_pk_mul_f32 v[194:195], v[10:11], v[150:151]
	v_pk_mul_f32 v[150:151], v[12:13], v[150:151]
	v_pk_mul_f32 v[148:149], v[148:149], v[152:153]
	v_pk_mul_f32 v[146:147], v[194:195], v[146:147]
	v_pk_mul_f32 v[148:149], v[150:151], v[148:149]
	v_cvt_pk_bf16_f32 v146, v146, v147
	v_cvt_pk_bf16_f32 v147, v148, v149
	global_store_dwordx2 v[226:227], v[146:147], off offset:8
	s_and_saveexec_b64 s[88:89], s[8:9]
	s_cbranch_execz .LBB0_986
	v_mov_b64_e32 v[146:147], s[66:67]
	v_mad_i64_i32 v[146:147], s[20:21], v245, s48, v[146:147]
	v_lshl_add_u64 v[146:147], v[168:169], 2, v[146:147]
	global_store_dwordx4 v[146:147], v[154:157], off offset:16
